# MLA: j0 rescale threshold add moved from before the masked/unmasked split into each path's QK MFMA cluster
# baseline (speedup 1.0000x reference)
; #define LAS __attribute__((address_space(3)))
; __device__ __forceinline__ float ex2(float x) { return __builtin_amdgcn_exp2f(x); }
; __device__ __forceinline__ f32x4 mfma16(bf16x8 a, bf16x8 b, f32x4 c) { return __builtin_amdgcn_mfma_f32_16x16x32_bf16(a, b, c, 0, 0, 0); }
;   __device__ __forceinline__ bf16_t* W() const { return (bf16_t*)(ws + WS_W); }
; template <int NT, int NKK, int NDT, int MODE, bool MASK> ...
;     ...
;   f32x4 s[NT][4];
;   __builtin_amdgcn_s_setprio(1);
; #pragma unroll
;   for (int t = 0; t < 4; ++t)
; #pragma unroll
;     for (int kk = 0; kk < NKK; ++kk) {
;       const bf16x8 kf = *(LAS const bf16x8*)(Kl + (16 * t + r) * KSTR + (32 * kk + 8 * lg) * 2);
; #pragma unroll
;       for (int j = 0; j < NT; ++j) s[j][t] = mfma16(kf, qf[j][kk], kk == 0 ? (f32x4){0.f, 0.f, 0.f, 0.f} : s[j][t]);
;     }
;   __builtin_amdgcn_s_setprio(0);
;   bf16x8 pf[NT][2];
; #pragma unroll
;   for (int j = 0; j < NT; ++j) {
;     float mx = -INFINITY;
; #pragma unroll
;     for (int t = 0; t < 4; ++t)
; #pragma unroll
;       for (int i = 0; i < 4; ++i) {
;         if (MASK) { const int kp = kpos0 + 16 * t + 4 * lg + i; if (!mask_ok<MODE>(tq[j], kp, W)) s[j][t][i] = -INFINITY; }
;         mx = fmaxf(mx, s[j][t][i]);
;       }
;     mx = max_x16_x32(mx);
;     if (__any(mx > m[j] + 8.0f / c)) {
;       const float mnew = fmaxf(m[j], mx);
;       const float ms2 = (mnew == -INFINITY) ? 0.f : mnew;
;       const float alpha = ex2((m[j] - ms2) * c);
;       m[j] = mnew; l[j] *= alpha;
; #pragma unroll
;       for (int dt = 0; dt < NDT; ++dt) o[j][dt] *= alpha;
;     }
;     const float mc = ((m[j] == -INFINITY) ? 0.f : m[j]) * c;
.LBB0_768:
	s_waitcnt lgkmcnt(0)
	s_barrier
	s_add_i32 s8, s69, 0xffffff41
	s_cmp_gt_i32 s8, s68
	s_cbranch_scc1 .LBB0_797
	s_add_i32 s8, s69, 0xffffff80
	s_cmp_gt_i32 s8, s59
	s_setprio 1
	v_add_u32_e32 v1, s71, v236
	s_waitcnt lgkmcnt(0)
	v_add_u32_e32 v94, v1, v237
	ds_read_b128 v[134:137], v94
	ds_read_b128 v[130:133], v94 offset:64
	ds_read_b128 v[126:129], v94 offset:128
	ds_read_b128 v[122:125], v94 offset:3328
	ds_read_b128 v[118:121], v94 offset:3392
	ds_read_b128 v[114:117], v94 offset:3456
	ds_read_b128 v[106:109], v94 offset:6656
	ds_read_b128 v[98:101], v94 offset:6720
	v_add_u32_e32 v201, v1, v238
	ds_read_b128 v[110:113], v94 offset:6784
	ds_read_b128 v[102:105], v201
	ds_read_b128 v[94:97], v201 offset:64
	s_mov_b64 s[20:21], -1
	s_cbranch_scc1 .LBB0_788
	s_waitcnt lgkmcnt(10)
	v_mfma_f32_16x16x32_bf16 v[138:141], v[134:137], v[18:21], 0
	v_add_f32_e32 v1, 0x4259535f, v220
	ds_read_b128 v[146:149], v201 offset:128
	v_mov_b32_e32 v234, 0x260
	v_mfma_f32_16x16x32_bf16 v[142:145], v[134:137], v[10:13], 0
	s_waitcnt lgkmcnt(10)
	v_mfma_f32_16x16x32_bf16 v[138:141], v[130:133], v[2:5], v[138:141]
	v_mov_b64_e32 v[222:223], v[220:221]
	v_mfma_f32_16x16x32_bf16 v[142:145], v[130:133], v[14:17], v[142:145]
	v_mov_b64_e32 v[224:225], v[218:219]
	s_waitcnt lgkmcnt(9)
	v_mfma_f32_16x16x32_bf16 v[182:185], v[126:129], v[6:9], v[138:141]
	v_mfma_f32_16x16x32_bf16 v[166:169], v[126:129], v[22:25], v[142:145]
	v_mov_b32_e32 v187, v220
	s_waitcnt lgkmcnt(8)
	v_mfma_f32_16x16x32_bf16 v[138:141], v[122:125], v[18:21], 0
	v_add_f32_e32 v158, 0x4259535f, v221
	v_mfma_f32_16x16x32_bf16 v[142:145], v[122:125], v[10:13], 0
	v_mul_f32_e32 v159, 0x3e16c740, v220
	s_waitcnt lgkmcnt(7)
	v_mfma_f32_16x16x32_bf16 v[138:141], v[118:121], v[2:5], v[138:141]
	v_cmp_neq_f32_e64 s[22:23], s81, v220
	v_mfma_f32_16x16x32_bf16 v[142:145], v[118:121], v[14:17], v[142:145]
	s_waitcnt lgkmcnt(6)
	v_mfma_f32_16x16x32_bf16 v[178:181], v[114:117], v[6:9], v[138:141]
	v_mfma_f32_16x16x32_bf16 v[154:157], v[114:117], v[22:25], v[142:145]
	v_cndmask_b32_e64 v159, 0, v159, s[22:23]
	s_waitcnt lgkmcnt(5)
	v_mfma_f32_16x16x32_bf16 v[138:141], v[106:109], v[18:21], 0
	v_mul_f32_e32 v160, 0x3e16c740, v221
	v_mfma_f32_16x16x32_bf16 v[142:145], v[106:109], v[10:13], 0
	v_cmp_neq_f32_e64 s[22:23], s81, v221
	v_max3_f32 v188, v182, s81, v183
	s_waitcnt lgkmcnt(4)
	v_mfma_f32_16x16x32_bf16 v[138:141], v[98:101], v[2:5], v[138:141]
	v_max3_f32 v188, v188, v184, v185
	v_mfma_f32_16x16x32_bf16 v[142:145], v[98:101], v[14:17], v[142:145]
	v_max3_f32 v189, v166, s81, v167
	s_waitcnt lgkmcnt(3)
	v_mfma_f32_16x16x32_bf16 v[174:177], v[110:113], v[6:9], v[138:141]
	v_cndmask_b32_e64 v160, 0, v160, s[22:23]
	v_max3_f32 v189, v189, v168, v169
	v_mfma_f32_16x16x32_bf16 v[150:153], v[110:113], v[22:25], v[142:145]
	s_waitcnt lgkmcnt(2)
	v_mfma_f32_16x16x32_bf16 v[138:141], v[102:105], v[18:21], 0
	v_mfma_f32_16x16x32_bf16 v[142:145], v[102:105], v[10:13], 0
	v_max3_f32 v188, v188, v178, v179
	s_waitcnt lgkmcnt(1)
	v_mfma_f32_16x16x32_bf16 v[138:141], v[94:97], v[2:5], v[138:141]
	v_max3_f32 v188, v188, v180, v181
	v_mfma_f32_16x16x32_bf16 v[142:145], v[94:97], v[14:17], v[142:145]
	v_max3_f32 v189, v189, v154, v155
	s_waitcnt lgkmcnt(0)
	v_mfma_f32_16x16x32_bf16 v[170:173], v[146:149], v[6:9], v[138:141]
	v_max3_f32 v189, v189, v156, v157
	v_mfma_f32_16x16x32_bf16 v[142:145], v[146:149], v[22:25], v[142:145]
	s_setprio 0
	s_nop 3
	v_max3_f32 v138, v188, v174, v175
	v_max3_f32 v138, v138, v176, v177
	v_max3_f32 v138, v138, v170, v171
	v_max3_f32 v138, v138, v172, v173
	v_mov_b32_e32 v139, v138
	s_nop 1
	v_permlane16_swap_b32_e32 v138, v139
	v_max_f32_e32 v138, v138, v139
	v_mov_b32_e32 v139, v138
	s_nop 1
	v_permlane32_swap_b32_e32 v138, v139
	v_max_f32_e32 v186, v138, v139
	v_cmp_gt_f32_e32 vcc, v186, v1
	s_cbranch_vccz .LBB0_772
	v_max_f32_e32 v138, v186, v186
	v_max_f32_e32 v139, v220, v220
	v_max_f32_e32 v222, v139, v138
	v_cmp_neq_f32_e32 vcc, s81, v222
	v_mov_b32_e32 v223, v221
	v_mov_b32_e32 v225, v219
	v_cndmask_b32_e32 v138, 0, v222, vcc
	v_sub_f32_e32 v138, v220, v138
	v_mul_f32_e32 v138, 0x3e16c740, v138
	v_exp_f32_e32 v138, v138
	v_mov_b32_e32 v187, v222
	v_mul_f32_e32 v224, v218, v138
	v_pk_mul_f32 v[92:93], v[92:93], v[138:139] op_sel_hi:[1,0]
	v_pk_mul_f32 v[90:91], v[90:91], v[138:139] op_sel_hi:[1,0]
	v_pk_mul_f32 v[88:89], v[88:89], v[138:139] op_sel_hi:[1,0]
	v_pk_mul_f32 v[86:87], v[86:87], v[138:139] op_sel_hi:[1,0]
	v_pk_mul_f32 v[76:77], v[76:77], v[138:139] op_sel_hi:[1,0]
	v_pk_mul_f32 v[74:75], v[74:75], v[138:139] op_sel_hi:[1,0]
	v_pk_mul_f32 v[68:69], v[68:69], v[138:139] op_sel_hi:[1,0]
	v_pk_mul_f32 v[66:67], v[66:67], v[138:139] op_sel_hi:[1,0]
	v_mul_f32_e32 v159, 0x3e16c740, v187
	v_cmp_neq_f32_e32 vcc, s81, v187
	s_nop 1
	v_cndmask_b32_e32 v159, 0, v159, vcc

; #define LAS __attribute__((address_space(3)))
; __device__ __forceinline__ float ex2(float x) { return __builtin_amdgcn_exp2f(x); }
; __device__ __forceinline__ f32x4 mfma16(bf16x8 a, bf16x8 b, f32x4 c) { return __builtin_amdgcn_mfma_f32_16x16x32_bf16(a, b, c, 0, 0, 0); }
;   __device__ __forceinline__ bf16_t* W() const { return (bf16_t*)(ws + WS_W); }
; template <int MODE> __device__ __forceinline__ bool mask_ok(int tq, int kp, int W) {
;   if (MODE == MODE_CAUSAL) return kp <= tq;
;   if (MODE == MODE_WINDOW) return kp <= tq && kp > tq - W;
; template <int NT, int NKK, int NDT, int MODE, bool MASK> ...
;     ...
;   f32x4 s[NT][4];
;   __builtin_amdgcn_s_setprio(1);
; #pragma unroll
;   for (int t = 0; t < 4; ++t)
; #pragma unroll
;     for (int kk = 0; kk < NKK; ++kk) {
;       const bf16x8 kf = *(LAS const bf16x8*)(Kl + (16 * t + r) * KSTR + (32 * kk + 8 * lg) * 2);
; #pragma unroll
;       for (int j = 0; j < NT; ++j) s[j][t] = mfma16(kf, qf[j][kk], kk == 0 ? (f32x4){0.f, 0.f, 0.f, 0.f} : s[j][t]);
;     }
;   __builtin_amdgcn_s_setprio(0);
;   bf16x8 pf[NT][2];
; #pragma unroll
;   for (int j = 0; j < NT; ++j) {
;     float mx = -INFINITY;
; #pragma unroll
;     for (int t = 0; t < 4; ++t)
; #pragma unroll
;       for (int i = 0; i < 4; ++i) {
;         if (MASK) { const int kp = kpos0 + 16 * t + 4 * lg + i; if (!mask_ok<MODE>(tq[j], kp, W)) s[j][t][i] = -INFINITY; }
;         mx = fmaxf(mx, s[j][t][i]);
;       }
;     mx = max_x16_x32(mx);
;     if (__any(mx > m[j] + 8.0f / c)) {
;       const float mnew = fmaxf(m[j], mx);
;       const float ms2 = (mnew == -INFINITY) ? 0.f : mnew;
;       const float alpha = ex2((m[j] - ms2) * c);
;       m[j] = mnew; l[j] *= alpha;
; #pragma unroll
;       for (int dt = 0; dt < NDT; ++dt) o[j][dt] *= alpha;
;     }
.LBB0_788:
	s_and_b64 vcc, exec, s[20:21]
	s_cbranch_vccz .LBB0_796
	v_add_f32_e32 v1, 0x4259535f, v220
	s_waitcnt lgkmcnt(10)
	v_mfma_f32_16x16x32_bf16 v[138:141], v[134:137], v[18:21], 0
	v_mfma_f32_16x16x32_bf16 v[134:137], v[134:137], v[10:13], 0
	s_waitcnt lgkmcnt(9)
	v_mfma_f32_16x16x32_bf16 v[138:141], v[130:133], v[2:5], v[138:141]
	v_mfma_f32_16x16x32_bf16 v[134:137], v[130:133], v[14:17], v[134:137]
	s_waitcnt lgkmcnt(8)
	v_mfma_f32_16x16x32_bf16 v[130:133], v[126:129], v[6:9], v[138:141]
	v_mfma_f32_16x16x32_bf16 v[126:129], v[126:129], v[22:25], v[134:137]
	s_waitcnt lgkmcnt(7)
	v_mfma_f32_16x16x32_bf16 v[134:137], v[122:125], v[18:21], 0
	v_mfma_f32_16x16x32_bf16 v[122:125], v[122:125], v[10:13], 0
	s_waitcnt lgkmcnt(6)
	v_mfma_f32_16x16x32_bf16 v[134:137], v[118:121], v[2:5], v[134:137]
	v_mfma_f32_16x16x32_bf16 v[118:121], v[118:121], v[14:17], v[122:125]
	s_waitcnt lgkmcnt(5)
	v_mfma_f32_16x16x32_bf16 v[134:137], v[114:117], v[6:9], v[134:137]
	v_mfma_f32_16x16x32_bf16 v[114:117], v[114:117], v[22:25], v[118:121]
	s_waitcnt lgkmcnt(4)
	v_mfma_f32_16x16x32_bf16 v[118:121], v[106:109], v[18:21], 0
	v_mfma_f32_16x16x32_bf16 v[106:109], v[106:109], v[10:13], 0
	s_waitcnt lgkmcnt(3)
	v_mfma_f32_16x16x32_bf16 v[118:121], v[98:101], v[2:5], v[118:121]
	v_mfma_f32_16x16x32_bf16 v[98:101], v[98:101], v[14:17], v[106:109]
	s_waitcnt lgkmcnt(1)
	v_mfma_f32_16x16x32_bf16 v[106:109], v[102:105], v[18:21], 0
	v_mfma_f32_16x16x32_bf16 v[102:105], v[102:105], v[10:13], 0
	s_waitcnt lgkmcnt(0)
	v_mfma_f32_16x16x32_bf16 v[106:109], v[94:97], v[2:5], v[106:109]
	v_mfma_f32_16x16x32_bf16 v[94:97], v[94:97], v[14:17], v[102:105]
	s_nop 4
	ds_read_b128 v[102:105], v201 offset:128
	v_mfma_f32_16x16x32_bf16 v[118:121], v[110:113], v[6:9], v[118:121]
	v_mfma_f32_16x16x32_bf16 v[98:101], v[110:113], v[22:25], v[98:101]
	s_waitcnt lgkmcnt(0)
	v_mfma_f32_16x16x32_bf16 v[94:97], v[102:105], v[22:25], v[94:97]
	v_mfma_f32_16x16x32_bf16 v[144:147], v[102:105], v[6:9], v[106:109]
	s_setprio 0
	v_add_u32_e32 v103, s69, v241
	v_add_u32_e32 v104, 0xffffff41, v103
	v_add_u32_e32 v105, 0xffffff43, v103
	v_mov_b32_e32 v102, s81
	v_cmp_gt_i32_e64 s[20:21], v104, v194
	v_cmp_lt_i32_e64 s[22:23], v104, v194
	v_cmp_le_i32_e32 vcc, v105, v194
	v_add_u32_e32 v106, 0xffffff44, v103
	v_cndmask_b32_e64 v142, v130, v102, s[20:21]
	v_cndmask_b32_e64 v122, v200, v131, s[22:23]
	v_cndmask_b32_e32 v124, v200, v132, vcc
	v_cmp_le_i32_e32 vcc, v106, v194
	v_max3_f32 v102, v142, s81, v122
	v_add_u32_e32 v107, 0xffffff51, v103
	v_cndmask_b32_e32 v123, v200, v133, vcc
	v_max3_f32 v108, v102, v124, v123
	v_mov_b32_e32 v102, s81
	v_cmp_gt_i32_e32 vcc, v107, v194
	v_add_u32_e32 v107, 0xffffff52, v103
	v_add_u32_e32 v110, 0xffffff54, v103
	v_cndmask_b32_e32 v125, v134, v102, vcc
	v_cmp_le_i32_e32 vcc, v107, v194
	v_add_u32_e32 v109, 0xffffff61, v103
	v_add_u32_e32 v111, 0xffffff62, v103
	v_cndmask_b32_e32 v131, v200, v135, vcc
	v_max3_f32 v102, v108, v125, v131
	v_add_u32_e32 v108, 0xffffff53, v103
	v_cmp_le_i32_e32 vcc, v108, v194
	v_add_u32_e32 v113, 0xffffff71, v103
	s_nop 0
	v_cndmask_b32_e32 v133, v200, v136, vcc
	v_cmp_le_i32_e32 vcc, v110, v194
	s_nop 1
	v_cndmask_b32_e32 v132, v200, v137, vcc
	v_max3_f32 v112, v102, v133, v132
	v_mov_b32_e32 v102, s81
	v_cmp_gt_i32_e32 vcc, v109, v194
	s_nop 1
	v_cndmask_b32_e32 v134, v118, v102, vcc
	v_cmp_le_i32_e32 vcc, v111, v194
	v_add_u32_e32 v118, 0xffffff64, v103
	s_nop 0
	v_cndmask_b32_e32 v135, v200, v119, vcc
	v_max3_f32 v102, v112, v134, v135
	v_add_u32_e32 v112, 0xffffff63, v103
	v_cmp_le_i32_e32 vcc, v112, v194
	v_add_u32_e32 v119, 0xffffff72, v103
	s_nop 0
	v_cndmask_b32_e32 v137, v200, v120, vcc
	v_cmp_le_i32_e32 vcc, v118, v194
	s_nop 1
	v_cndmask_b32_e32 v136, v200, v121, vcc
	v_max3_f32 v120, v102, v137, v136
	v_mov_b32_e32 v102, s81
	v_cmp_gt_i32_e32 vcc, v113, v194
	v_add_u32_e32 v121, 0xffffff74, v103
	s_nop 0
	v_cndmask_b32_e32 v138, v144, v102, vcc
	v_cmp_le_i32_e32 vcc, v119, v194
	s_nop 1
	v_cndmask_b32_e32 v139, v200, v145, vcc
	v_max3_f32 v102, v120, v138, v139
	v_add_u32_e32 v120, 0xffffff73, v103
	v_cmp_le_i32_e32 vcc, v120, v194
	s_nop 1
	v_cndmask_b32_e32 v141, v200, v146, vcc
	v_cmp_le_i32_e32 vcc, v121, v194
	s_nop 1
	v_cndmask_b32_e32 v140, v200, v147, vcc
	v_max3_f32 v102, v102, v141, v140
	v_mov_b32_e32 v103, v102
	s_nop 1
	v_permlane16_swap_b32_e32 v102, v103
	v_max_f32_e32 v102, v102, v103
	v_mov_b32_e32 v103, v102
	s_nop 1
	v_permlane32_swap_b32_e32 v102, v103
	v_max_f32_e32 v102, v102, v103
	v_cmp_gt_f32_e32 vcc, v102, v1
	s_cbranch_vccz .LBB0_791
	v_max_f32_e32 v1, v102, v102
	v_max_f32_e32 v102, v220, v220
	v_max_f32_e32 v102, v102, v1
	v_cmp_neq_f32_e32 vcc, s81, v102
	v_mov_b32_e32 v103, v221
	s_nop 0
	v_cndmask_b32_e32 v1, 0, v102, vcc
	v_sub_f32_e32 v1, v220, v1
	v_mul_f32_e32 v1, 0x3e16c740, v1
	v_exp_f32_e32 v144, v1
	v_mov_b64_e32 v[220:221], v[102:103]
	v_mul_f32_e32 v218, v218, v144
	v_pk_mul_f32 v[92:93], v[92:93], v[144:145] op_sel_hi:[1,0]
	v_pk_mul_f32 v[90:91], v[90:91], v[144:145] op_sel_hi:[1,0]
	v_pk_mul_f32 v[88:89], v[88:89], v[144:145] op_sel_hi:[1,0]
	v_pk_mul_f32 v[86:87], v[86:87], v[144:145] op_sel_hi:[1,0]
	v_pk_mul_f32 v[76:77], v[76:77], v[144:145] op_sel_hi:[1,0]
	v_pk_mul_f32 v[74:75], v[74:75], v[144:145] op_sel_hi:[1,0]
	v_pk_mul_f32 v[68:69], v[68:69], v[144:145] op_sel_hi:[1,0]
	v_pk_mul_f32 v[66:67], v[66:67], v[144:145] op_sel_hi:[1,0]
	s_branch .LBB0_792

; #define LAS __attribute__((address_space(3)))
; __device__ __forceinline__ float ex2(float x) { return __builtin_amdgcn_exp2f(x); }
; __device__ __forceinline__ f32x4 mfma16(bf16x8 a, bf16x8 b, f32x4 c) { return __builtin_amdgcn_mfma_f32_16x16x32_bf16(a, b, c, 0, 0, 0); }
;   __device__ __forceinline__ bf16_t* W() const { return (bf16_t*)(ws + WS_W); }
; template <int NT, int NKK, int NDT, int MODE, bool MASK> ...
;     ...
;   f32x4 s[NT][4];
;   __builtin_amdgcn_s_setprio(1);
; #pragma unroll
;   for (int t = 0; t < 4; ++t)
; #pragma unroll
;     for (int kk = 0; kk < NKK; ++kk) {
;       const bf16x8 kf = *(LAS const bf16x8*)(Kl + (16 * t + r) * KSTR + (32 * kk + 8 * lg) * 2);
; #pragma unroll
;       for (int j = 0; j < NT; ++j) s[j][t] = mfma16(kf, qf[j][kk], kk == 0 ? (f32x4){0.f, 0.f, 0.f, 0.f} : s[j][t]);
;     }
;   __builtin_amdgcn_s_setprio(0);
;   bf16x8 pf[NT][2];
; #pragma unroll
;   for (int j = 0; j < NT; ++j) {
;     float mx = -INFINITY;
; #pragma unroll
;     for (int t = 0; t < 4; ++t)
; #pragma unroll
;       for (int i = 0; i < 4; ++i) {
;         if (MASK) { const int kp = kpos0 + 16 * t + 4 * lg + i; if (!mask_ok<MODE>(tq[j], kp, W)) s[j][t][i] = -INFINITY; }
;         mx = fmaxf(mx, s[j][t][i]);
;       }
;     mx = max_x16_x32(mx);
;     if (__any(mx > m[j] + 8.0f / c)) {
;       const float mnew = fmaxf(m[j], mx);
;       const float ms2 = (mnew == -INFINITY) ? 0.f : mnew;
;       const float alpha = ex2((m[j] - ms2) * c);
;       m[j] = mnew; l[j] *= alpha;
; #pragma unroll
;       for (int dt = 0; dt < NDT; ++dt) o[j][dt] *= alpha;
;     }
;     const float mc = ((m[j] == -INFINITY) ? 0.f : m[j]) * c;
.LBB0_810:
	s_waitcnt lgkmcnt(0)
	s_barrier
	s_add_i32 s8, s69, 0xffffff81
	s_cmp_gt_i32 s8, s68
	s_cbranch_scc1 .LBB0_837
	s_sub_i32 s8, s69, 64
	s_cmp_gt_i32 s8, s59
	s_setprio 1
	v_add_u32_e32 v1, s73, v236
	s_waitcnt lgkmcnt(0)
	v_add_u32_e32 v94, v1, v237
	ds_read_b128 v[134:137], v94
	ds_read_b128 v[130:133], v94 offset:64
	ds_read_b128 v[126:129], v94 offset:128
	ds_read_b128 v[122:125], v94 offset:3328
	ds_read_b128 v[118:121], v94 offset:3392
	ds_read_b128 v[114:117], v94 offset:3456
	ds_read_b128 v[106:109], v94 offset:6656
	ds_read_b128 v[98:101], v94 offset:6720
	v_add_u32_e32 v201, v1, v238
	ds_read_b128 v[110:113], v94 offset:6784
	ds_read_b128 v[102:105], v201
	ds_read_b128 v[94:97], v201 offset:64
	s_mov_b64 s[20:21], -1
	s_cbranch_scc1 .LBB0_828
	s_waitcnt lgkmcnt(10)
	v_mfma_f32_16x16x32_bf16 v[138:141], v[134:137], v[18:21], 0
	v_add_f32_e32 v1, 0x4259535f, v220
	ds_read_b128 v[146:149], v201 offset:128
	v_mov_b32_e32 v234, 0x260
	v_mfma_f32_16x16x32_bf16 v[142:145], v[134:137], v[10:13], 0
	s_waitcnt lgkmcnt(10)
	v_mfma_f32_16x16x32_bf16 v[138:141], v[130:133], v[2:5], v[138:141]
	v_mov_b64_e32 v[222:223], v[220:221]
	v_mfma_f32_16x16x32_bf16 v[142:145], v[130:133], v[14:17], v[142:145]
	v_mov_b64_e32 v[224:225], v[218:219]
	s_waitcnt lgkmcnt(9)
	v_mfma_f32_16x16x32_bf16 v[182:185], v[126:129], v[6:9], v[138:141]
	v_mfma_f32_16x16x32_bf16 v[166:169], v[126:129], v[22:25], v[142:145]
	v_mov_b32_e32 v187, v220
	s_waitcnt lgkmcnt(8)
	v_mfma_f32_16x16x32_bf16 v[138:141], v[122:125], v[18:21], 0
	v_add_f32_e32 v158, 0x4259535f, v221
	v_mfma_f32_16x16x32_bf16 v[142:145], v[122:125], v[10:13], 0
	v_mul_f32_e32 v159, 0x3e16c740, v220
	s_waitcnt lgkmcnt(7)
	v_mfma_f32_16x16x32_bf16 v[138:141], v[118:121], v[2:5], v[138:141]
	v_cmp_neq_f32_e64 s[22:23], s81, v220
	v_mfma_f32_16x16x32_bf16 v[142:145], v[118:121], v[14:17], v[142:145]
	s_waitcnt lgkmcnt(6)
	v_mfma_f32_16x16x32_bf16 v[178:181], v[114:117], v[6:9], v[138:141]
	v_mfma_f32_16x16x32_bf16 v[154:157], v[114:117], v[22:25], v[142:145]
	v_cndmask_b32_e64 v159, 0, v159, s[22:23]
	s_waitcnt lgkmcnt(5)
	v_mfma_f32_16x16x32_bf16 v[138:141], v[106:109], v[18:21], 0
	v_mul_f32_e32 v160, 0x3e16c740, v221
	v_mfma_f32_16x16x32_bf16 v[142:145], v[106:109], v[10:13], 0
	v_cmp_neq_f32_e64 s[22:23], s81, v221
	v_max3_f32 v188, v182, s81, v183
	s_waitcnt lgkmcnt(4)
	v_mfma_f32_16x16x32_bf16 v[138:141], v[98:101], v[2:5], v[138:141]
	v_max3_f32 v188, v188, v184, v185
	v_mfma_f32_16x16x32_bf16 v[142:145], v[98:101], v[14:17], v[142:145]
	v_max3_f32 v189, v166, s81, v167
	s_waitcnt lgkmcnt(3)
	v_mfma_f32_16x16x32_bf16 v[174:177], v[110:113], v[6:9], v[138:141]
	v_cndmask_b32_e64 v160, 0, v160, s[22:23]
	v_max3_f32 v189, v189, v168, v169
	v_mfma_f32_16x16x32_bf16 v[150:153], v[110:113], v[22:25], v[142:145]
	s_waitcnt lgkmcnt(2)
	v_mfma_f32_16x16x32_bf16 v[138:141], v[102:105], v[18:21], 0
	v_mfma_f32_16x16x32_bf16 v[142:145], v[102:105], v[10:13], 0
	v_max3_f32 v188, v188, v178, v179
	s_waitcnt lgkmcnt(1)
	v_mfma_f32_16x16x32_bf16 v[138:141], v[94:97], v[2:5], v[138:141]
	v_max3_f32 v188, v188, v180, v181
	v_mfma_f32_16x16x32_bf16 v[142:145], v[94:97], v[14:17], v[142:145]
	v_max3_f32 v189, v189, v154, v155
	s_waitcnt lgkmcnt(0)
	v_mfma_f32_16x16x32_bf16 v[170:173], v[146:149], v[6:9], v[138:141]
	v_max3_f32 v189, v189, v156, v157
	v_mfma_f32_16x16x32_bf16 v[142:145], v[146:149], v[22:25], v[142:145]
	s_setprio 0
	s_nop 3
	v_max3_f32 v138, v188, v174, v175
	v_max3_f32 v138, v138, v176, v177
	v_max3_f32 v138, v138, v170, v171
	v_max3_f32 v138, v138, v172, v173
	v_mov_b32_e32 v139, v138
	s_nop 1
	v_permlane16_swap_b32_e32 v138, v139
	v_max_f32_e32 v138, v138, v139
	v_mov_b32_e32 v139, v138
	s_nop 1
	v_permlane32_swap_b32_e32 v138, v139
	v_max_f32_e32 v186, v138, v139
	v_cmp_gt_f32_e32 vcc, v186, v1
	s_cbranch_vccz .LBB0_814
	v_max_f32_e32 v138, v186, v186
	v_max_f32_e32 v139, v220, v220
	v_max_f32_e32 v222, v139, v138
	v_cmp_neq_f32_e32 vcc, s81, v222
	v_mov_b32_e32 v223, v221
	v_mov_b32_e32 v225, v219
	v_cndmask_b32_e32 v138, 0, v222, vcc
	v_sub_f32_e32 v138, v220, v138
	v_mul_f32_e32 v138, 0x3e16c740, v138
	v_exp_f32_e32 v138, v138
	v_mov_b32_e32 v187, v222
	v_mul_f32_e32 v224, v218, v138
	v_pk_mul_f32 v[92:93], v[92:93], v[138:139] op_sel_hi:[1,0]
	v_pk_mul_f32 v[90:91], v[90:91], v[138:139] op_sel_hi:[1,0]
	v_pk_mul_f32 v[88:89], v[88:89], v[138:139] op_sel_hi:[1,0]
	v_pk_mul_f32 v[86:87], v[86:87], v[138:139] op_sel_hi:[1,0]
	v_pk_mul_f32 v[76:77], v[76:77], v[138:139] op_sel_hi:[1,0]
	v_pk_mul_f32 v[74:75], v[74:75], v[138:139] op_sel_hi:[1,0]
	v_pk_mul_f32 v[68:69], v[68:69], v[138:139] op_sel_hi:[1,0]
	v_pk_mul_f32 v[66:67], v[66:67], v[138:139] op_sel_hi:[1,0]
	v_mul_f32_e32 v159, 0x3e16c740, v187
	v_cmp_neq_f32_e32 vcc, s81, v187
	s_nop 1
	v_cndmask_b32_e32 v159, 0, v159, vcc

; #define LAS __attribute__((address_space(3)))
; __device__ __forceinline__ float ex2(float x) { return __builtin_amdgcn_exp2f(x); }
; __device__ __forceinline__ f32x4 mfma16(bf16x8 a, bf16x8 b, f32x4 c) { return __builtin_amdgcn_mfma_f32_16x16x32_bf16(a, b, c, 0, 0, 0); }
;   __device__ __forceinline__ bf16_t* W() const { return (bf16_t*)(ws + WS_W); }
; template <int MODE> __device__ __forceinline__ bool mask_ok(int tq, int kp, int W) {
;   if (MODE == MODE_CAUSAL) return kp <= tq;
;   if (MODE == MODE_WINDOW) return kp <= tq && kp > tq - W;
; template <int NT, int NKK, int NDT, int MODE, bool MASK> ...
;     ...
;   f32x4 s[NT][4];
;   __builtin_amdgcn_s_setprio(1);
; #pragma unroll
;   for (int t = 0; t < 4; ++t)
; #pragma unroll
;     for (int kk = 0; kk < NKK; ++kk) {
;       const bf16x8 kf = *(LAS const bf16x8*)(Kl + (16 * t + r) * KSTR + (32 * kk + 8 * lg) * 2);
; #pragma unroll
;       for (int j = 0; j < NT; ++j) s[j][t] = mfma16(kf, qf[j][kk], kk == 0 ? (f32x4){0.f, 0.f, 0.f, 0.f} : s[j][t]);
;     }
;   __builtin_amdgcn_s_setprio(0);
;   bf16x8 pf[NT][2];
; #pragma unroll
;   for (int j = 0; j < NT; ++j) {
;     float mx = -INFINITY;
; #pragma unroll
;     for (int t = 0; t < 4; ++t)
; #pragma unroll
;       for (int i = 0; i < 4; ++i) {
;         if (MASK) { const int kp = kpos0 + 16 * t + 4 * lg + i; if (!mask_ok<MODE>(tq[j], kp, W)) s[j][t][i] = -INFINITY; }
;         mx = fmaxf(mx, s[j][t][i]);
;       }
;     mx = max_x16_x32(mx);
;     if (__any(mx > m[j] + 8.0f / c)) {
;       const float mnew = fmaxf(m[j], mx);
;       const float ms2 = (mnew == -INFINITY) ? 0.f : mnew;
;       const float alpha = ex2((m[j] - ms2) * c);
;       m[j] = mnew; l[j] *= alpha;
; #pragma unroll
;       for (int dt = 0; dt < NDT; ++dt) o[j][dt] *= alpha;
;     }
.LBB0_828:
	s_and_b64 vcc, exec, s[20:21]
	s_cbranch_vccz .LBB0_836
	v_add_f32_e32 v1, 0x4259535f, v220
	s_waitcnt lgkmcnt(10)
	v_mfma_f32_16x16x32_bf16 v[138:141], v[134:137], v[18:21], 0
	v_mfma_f32_16x16x32_bf16 v[134:137], v[134:137], v[10:13], 0
	s_waitcnt lgkmcnt(9)
	v_mfma_f32_16x16x32_bf16 v[138:141], v[130:133], v[2:5], v[138:141]
	v_mfma_f32_16x16x32_bf16 v[134:137], v[130:133], v[14:17], v[134:137]
	s_waitcnt lgkmcnt(8)
	v_mfma_f32_16x16x32_bf16 v[130:133], v[126:129], v[6:9], v[138:141]
	v_mfma_f32_16x16x32_bf16 v[126:129], v[126:129], v[22:25], v[134:137]
	s_waitcnt lgkmcnt(7)
	v_mfma_f32_16x16x32_bf16 v[134:137], v[122:125], v[18:21], 0
	v_mfma_f32_16x16x32_bf16 v[122:125], v[122:125], v[10:13], 0
	s_waitcnt lgkmcnt(6)
	v_mfma_f32_16x16x32_bf16 v[134:137], v[118:121], v[2:5], v[134:137]
	v_mfma_f32_16x16x32_bf16 v[118:121], v[118:121], v[14:17], v[122:125]
	s_waitcnt lgkmcnt(5)
	v_mfma_f32_16x16x32_bf16 v[134:137], v[114:117], v[6:9], v[134:137]
	v_mfma_f32_16x16x32_bf16 v[114:117], v[114:117], v[22:25], v[118:121]
	s_waitcnt lgkmcnt(4)
	v_mfma_f32_16x16x32_bf16 v[118:121], v[106:109], v[18:21], 0
	v_mfma_f32_16x16x32_bf16 v[106:109], v[106:109], v[10:13], 0
	s_waitcnt lgkmcnt(3)
	v_mfma_f32_16x16x32_bf16 v[118:121], v[98:101], v[2:5], v[118:121]
	v_mfma_f32_16x16x32_bf16 v[98:101], v[98:101], v[14:17], v[106:109]
	s_waitcnt lgkmcnt(1)
	v_mfma_f32_16x16x32_bf16 v[106:109], v[102:105], v[18:21], 0
	v_mfma_f32_16x16x32_bf16 v[102:105], v[102:105], v[10:13], 0
	s_waitcnt lgkmcnt(0)
	v_mfma_f32_16x16x32_bf16 v[106:109], v[94:97], v[2:5], v[106:109]
	v_mfma_f32_16x16x32_bf16 v[94:97], v[94:97], v[14:17], v[102:105]
	s_nop 4
	ds_read_b128 v[102:105], v201 offset:128
	v_mfma_f32_16x16x32_bf16 v[118:121], v[110:113], v[6:9], v[118:121]
	v_mfma_f32_16x16x32_bf16 v[98:101], v[110:113], v[22:25], v[98:101]
	s_waitcnt lgkmcnt(0)
	v_mfma_f32_16x16x32_bf16 v[94:97], v[102:105], v[22:25], v[94:97]
	v_mfma_f32_16x16x32_bf16 v[144:147], v[102:105], v[6:9], v[106:109]
	s_setprio 0
	v_add_u32_e32 v103, s69, v241
	v_add_u32_e32 v104, 0xffffff81, v103
	v_add_u32_e32 v105, 0xffffff83, v103
	v_mov_b32_e32 v102, s81
	v_cmp_gt_i32_e64 s[20:21], v104, v194
	v_cmp_lt_i32_e64 s[22:23], v104, v194
	v_cmp_le_i32_e32 vcc, v105, v194
	v_add_u32_e32 v106, 0xffffff84, v103
	v_cndmask_b32_e64 v142, v130, v102, s[20:21]
	v_cndmask_b32_e64 v122, v200, v131, s[22:23]
	v_cndmask_b32_e32 v124, v200, v132, vcc
	v_cmp_le_i32_e32 vcc, v106, v194
	v_max3_f32 v102, v142, s81, v122
	v_add_u32_e32 v107, 0xffffff91, v103
	v_cndmask_b32_e32 v123, v200, v133, vcc
	v_max3_f32 v108, v102, v124, v123
	v_mov_b32_e32 v102, s81
	v_cmp_gt_i32_e32 vcc, v107, v194
	v_add_u32_e32 v107, 0xffffff92, v103
	v_add_u32_e32 v110, 0xffffff94, v103
	v_cndmask_b32_e32 v125, v134, v102, vcc
	v_cmp_le_i32_e32 vcc, v107, v194
	v_add_u32_e32 v109, 0xffffffa1, v103
	v_add_u32_e32 v111, 0xffffffa2, v103
	v_cndmask_b32_e32 v131, v200, v135, vcc
	v_max3_f32 v102, v108, v125, v131
	v_add_u32_e32 v108, 0xffffff93, v103
	v_cmp_le_i32_e32 vcc, v108, v194
	v_add_u32_e32 v113, 0xffffffb1, v103
	s_nop 0
	v_cndmask_b32_e32 v133, v200, v136, vcc
	v_cmp_le_i32_e32 vcc, v110, v194
	s_nop 1
	v_cndmask_b32_e32 v132, v200, v137, vcc
	v_max3_f32 v112, v102, v133, v132
	v_mov_b32_e32 v102, s81
	v_cmp_gt_i32_e32 vcc, v109, v194
	s_nop 1
	v_cndmask_b32_e32 v134, v118, v102, vcc
	v_cmp_le_i32_e32 vcc, v111, v194
	v_add_u32_e32 v118, 0xffffffa4, v103
	s_nop 0
	v_cndmask_b32_e32 v135, v200, v119, vcc
	v_max3_f32 v102, v112, v134, v135
	v_add_u32_e32 v112, 0xffffffa3, v103
	v_cmp_le_i32_e32 vcc, v112, v194
	v_add_u32_e32 v119, 0xffffffb2, v103
	s_nop 0
	v_cndmask_b32_e32 v137, v200, v120, vcc
	v_cmp_le_i32_e32 vcc, v118, v194
	s_nop 1
	v_cndmask_b32_e32 v136, v200, v121, vcc
	v_max3_f32 v120, v102, v137, v136
	v_mov_b32_e32 v102, s81
	v_cmp_gt_i32_e32 vcc, v113, v194
	v_add_u32_e32 v121, 0xffffffb4, v103
	s_nop 0
	v_cndmask_b32_e32 v138, v144, v102, vcc
	v_cmp_le_i32_e32 vcc, v119, v194
	s_nop 1
	v_cndmask_b32_e32 v139, v200, v145, vcc
	v_max3_f32 v102, v120, v138, v139
	v_add_u32_e32 v120, 0xffffffb3, v103
	v_cmp_le_i32_e32 vcc, v120, v194
	s_nop 1
	v_cndmask_b32_e32 v141, v200, v146, vcc
	v_cmp_le_i32_e32 vcc, v121, v194
	s_nop 1
	v_cndmask_b32_e32 v140, v200, v147, vcc
	v_max3_f32 v102, v102, v141, v140
	v_mov_b32_e32 v103, v102
	s_nop 1
	v_permlane16_swap_b32_e32 v102, v103
	v_max_f32_e32 v102, v102, v103
	v_mov_b32_e32 v103, v102
	s_nop 1
	v_permlane32_swap_b32_e32 v102, v103
	v_max_f32_e32 v102, v102, v103
	v_cmp_gt_f32_e32 vcc, v102, v1
	s_cbranch_vccz .LBB0_831
	v_max_f32_e32 v1, v102, v102
	v_max_f32_e32 v102, v220, v220
	v_max_f32_e32 v102, v102, v1
	v_cmp_neq_f32_e32 vcc, s81, v102
	v_mov_b32_e32 v103, v221
	s_nop 0
	v_cndmask_b32_e32 v1, 0, v102, vcc
	v_sub_f32_e32 v1, v220, v1
	v_mul_f32_e32 v1, 0x3e16c740, v1
	v_exp_f32_e32 v144, v1
	v_mov_b64_e32 v[220:221], v[102:103]
	v_mul_f32_e32 v218, v218, v144
	v_pk_mul_f32 v[92:93], v[92:93], v[144:145] op_sel_hi:[1,0]
	v_pk_mul_f32 v[90:91], v[90:91], v[144:145] op_sel_hi:[1,0]
	v_pk_mul_f32 v[88:89], v[88:89], v[144:145] op_sel_hi:[1,0]
	v_pk_mul_f32 v[86:87], v[86:87], v[144:145] op_sel_hi:[1,0]
	v_pk_mul_f32 v[76:77], v[76:77], v[144:145] op_sel_hi:[1,0]
	v_pk_mul_f32 v[74:75], v[74:75], v[144:145] op_sel_hi:[1,0]
	v_pk_mul_f32 v[68:69], v[68:69], v[144:145] op_sel_hi:[1,0]
	v_pk_mul_f32 v[66:67], v[66:67], v[144:145] op_sel_hi:[1,0]
	s_branch .LBB0_832

; #define LAS __attribute__((address_space(3)))
; __device__ __forceinline__ float ex2(float x) { return __builtin_amdgcn_exp2f(x); }
; __device__ __forceinline__ f32x4 mfma16(bf16x8 a, bf16x8 b, f32x4 c) { return __builtin_amdgcn_mfma_f32_16x16x32_bf16(a, b, c, 0, 0, 0); }
;   __device__ __forceinline__ bf16_t* W() const { return (bf16_t*)(ws + WS_W); }
; template <int NT, int NKK, int NDT, int MODE, bool MASK> ...
;     ...
;   f32x4 s[NT][4];
;   __builtin_amdgcn_s_setprio(1);
; #pragma unroll
;   for (int t = 0; t < 4; ++t)
; #pragma unroll
;     for (int kk = 0; kk < NKK; ++kk) {
;       const bf16x8 kf = *(LAS const bf16x8*)(Kl + (16 * t + r) * KSTR + (32 * kk + 8 * lg) * 2);
; #pragma unroll
;       for (int j = 0; j < NT; ++j) s[j][t] = mfma16(kf, qf[j][kk], kk == 0 ? (f32x4){0.f, 0.f, 0.f, 0.f} : s[j][t]);
;     }
;   __builtin_amdgcn_s_setprio(0);
;   bf16x8 pf[NT][2];
; #pragma unroll
;   for (int j = 0; j < NT; ++j) {
;     float mx = -INFINITY;
; #pragma unroll
;     for (int t = 0; t < 4; ++t)
; #pragma unroll
;       for (int i = 0; i < 4; ++i) {
;         if (MASK) { const int kp = kpos0 + 16 * t + 4 * lg + i; if (!mask_ok<MODE>(tq[j], kp, W)) s[j][t][i] = -INFINITY; }
;         mx = fmaxf(mx, s[j][t][i]);
;       }
;     mx = max_x16_x32(mx);
;     if (__any(mx > m[j] + 8.0f / c)) {
;       const float mnew = fmaxf(m[j], mx);
;       const float ms2 = (mnew == -INFINITY) ? 0.f : mnew;
;       const float alpha = ex2((m[j] - ms2) * c);
;       m[j] = mnew; l[j] *= alpha;
; #pragma unroll
;       for (int dt = 0; dt < NDT; ++dt) o[j][dt] *= alpha;
;     }
;     const float mc = ((m[j] == -INFINITY) ? 0.f : m[j]) * c;
.LBB0_850:
	s_waitcnt lgkmcnt(0)
	s_barrier
	s_sub_i32 s8, s69, 63
	s_cmp_gt_i32 s8, s68
	s_cbranch_scc1 .LBB0_877
	s_cmp_gt_i32 s69, s59
	s_setprio 1
	v_add_u32_e32 v1, s71, v236
	s_waitcnt lgkmcnt(0)
	v_add_u32_e32 v94, v1, v237
	ds_read_b128 v[134:137], v94
	ds_read_b128 v[130:133], v94 offset:64
	ds_read_b128 v[126:129], v94 offset:128
	ds_read_b128 v[122:125], v94 offset:3328
	ds_read_b128 v[118:121], v94 offset:3392
	ds_read_b128 v[114:117], v94 offset:3456
	ds_read_b128 v[106:109], v94 offset:6656
	ds_read_b128 v[98:101], v94 offset:6720
	v_add_u32_e32 v201, v1, v238
	ds_read_b128 v[110:113], v94 offset:6784
	ds_read_b128 v[102:105], v201
	ds_read_b128 v[94:97], v201 offset:64
	s_mov_b64 s[20:21], -1
	s_cbranch_scc1 .LBB0_868
	s_waitcnt lgkmcnt(10)
	v_mfma_f32_16x16x32_bf16 v[138:141], v[134:137], v[18:21], 0
	v_add_f32_e32 v1, 0x4259535f, v220
	ds_read_b128 v[146:149], v201 offset:128
	v_mov_b32_e32 v234, 0x260
	v_mfma_f32_16x16x32_bf16 v[142:145], v[134:137], v[10:13], 0
	s_waitcnt lgkmcnt(10)
	v_mfma_f32_16x16x32_bf16 v[138:141], v[130:133], v[2:5], v[138:141]
	v_mov_b64_e32 v[222:223], v[220:221]
	v_mfma_f32_16x16x32_bf16 v[142:145], v[130:133], v[14:17], v[142:145]
	v_mov_b64_e32 v[224:225], v[218:219]
	s_waitcnt lgkmcnt(9)
	v_mfma_f32_16x16x32_bf16 v[182:185], v[126:129], v[6:9], v[138:141]
	v_mfma_f32_16x16x32_bf16 v[166:169], v[126:129], v[22:25], v[142:145]
	v_mov_b32_e32 v187, v220
	s_waitcnt lgkmcnt(8)
	v_mfma_f32_16x16x32_bf16 v[138:141], v[122:125], v[18:21], 0
	v_add_f32_e32 v158, 0x4259535f, v221
	v_mfma_f32_16x16x32_bf16 v[142:145], v[122:125], v[10:13], 0
	v_mul_f32_e32 v159, 0x3e16c740, v220
	s_waitcnt lgkmcnt(7)
	v_mfma_f32_16x16x32_bf16 v[138:141], v[118:121], v[2:5], v[138:141]
	v_cmp_neq_f32_e64 s[22:23], s81, v220
	v_mfma_f32_16x16x32_bf16 v[142:145], v[118:121], v[14:17], v[142:145]
	s_waitcnt lgkmcnt(6)
	v_mfma_f32_16x16x32_bf16 v[178:181], v[114:117], v[6:9], v[138:141]
	v_mfma_f32_16x16x32_bf16 v[154:157], v[114:117], v[22:25], v[142:145]
	v_cndmask_b32_e64 v159, 0, v159, s[22:23]
	s_waitcnt lgkmcnt(5)
	v_mfma_f32_16x16x32_bf16 v[138:141], v[106:109], v[18:21], 0
	v_mul_f32_e32 v160, 0x3e16c740, v221
	v_mfma_f32_16x16x32_bf16 v[142:145], v[106:109], v[10:13], 0
	v_cmp_neq_f32_e64 s[22:23], s81, v221
	v_max3_f32 v188, v182, s81, v183
	s_waitcnt lgkmcnt(4)
	v_mfma_f32_16x16x32_bf16 v[138:141], v[98:101], v[2:5], v[138:141]
	v_max3_f32 v188, v188, v184, v185
	v_mfma_f32_16x16x32_bf16 v[142:145], v[98:101], v[14:17], v[142:145]
	v_max3_f32 v189, v166, s81, v167
	s_waitcnt lgkmcnt(3)
	v_mfma_f32_16x16x32_bf16 v[174:177], v[110:113], v[6:9], v[138:141]
	v_cndmask_b32_e64 v160, 0, v160, s[22:23]
	v_max3_f32 v189, v189, v168, v169
	v_mfma_f32_16x16x32_bf16 v[150:153], v[110:113], v[22:25], v[142:145]
	s_waitcnt lgkmcnt(2)
	v_mfma_f32_16x16x32_bf16 v[138:141], v[102:105], v[18:21], 0
	v_mfma_f32_16x16x32_bf16 v[142:145], v[102:105], v[10:13], 0
	v_max3_f32 v188, v188, v178, v179
	s_waitcnt lgkmcnt(1)
	v_mfma_f32_16x16x32_bf16 v[138:141], v[94:97], v[2:5], v[138:141]
	v_max3_f32 v188, v188, v180, v181
	v_mfma_f32_16x16x32_bf16 v[142:145], v[94:97], v[14:17], v[142:145]
	v_max3_f32 v189, v189, v154, v155
	s_waitcnt lgkmcnt(0)
	v_mfma_f32_16x16x32_bf16 v[170:173], v[146:149], v[6:9], v[138:141]
	v_max3_f32 v189, v189, v156, v157
	v_mfma_f32_16x16x32_bf16 v[142:145], v[146:149], v[22:25], v[142:145]
	s_setprio 0
	s_nop 3
	v_max3_f32 v138, v188, v174, v175
	v_max3_f32 v138, v138, v176, v177
	v_max3_f32 v138, v138, v170, v171
	v_max3_f32 v138, v138, v172, v173
	v_mov_b32_e32 v139, v138
	s_nop 1
	v_permlane16_swap_b32_e32 v138, v139
	v_max_f32_e32 v138, v138, v139
	v_mov_b32_e32 v139, v138
	s_nop 1
	v_permlane32_swap_b32_e32 v138, v139
	v_max_f32_e32 v186, v138, v139
	v_cmp_gt_f32_e32 vcc, v186, v1
	s_cbranch_vccz .LBB0_854
	v_max_f32_e32 v138, v186, v186
	v_max_f32_e32 v139, v220, v220
	v_max_f32_e32 v222, v139, v138
	v_cmp_neq_f32_e32 vcc, s81, v222
	v_mov_b32_e32 v223, v221
	v_mov_b32_e32 v225, v219
	v_cndmask_b32_e32 v138, 0, v222, vcc
	v_sub_f32_e32 v138, v220, v138
	v_mul_f32_e32 v138, 0x3e16c740, v138
	v_exp_f32_e32 v138, v138
	v_mov_b32_e32 v187, v222
	v_mul_f32_e32 v224, v218, v138
	v_pk_mul_f32 v[92:93], v[92:93], v[138:139] op_sel_hi:[1,0]
	v_pk_mul_f32 v[90:91], v[90:91], v[138:139] op_sel_hi:[1,0]
	v_pk_mul_f32 v[88:89], v[88:89], v[138:139] op_sel_hi:[1,0]
	v_pk_mul_f32 v[86:87], v[86:87], v[138:139] op_sel_hi:[1,0]
	v_pk_mul_f32 v[76:77], v[76:77], v[138:139] op_sel_hi:[1,0]
	v_pk_mul_f32 v[74:75], v[74:75], v[138:139] op_sel_hi:[1,0]
	v_pk_mul_f32 v[68:69], v[68:69], v[138:139] op_sel_hi:[1,0]
	v_pk_mul_f32 v[66:67], v[66:67], v[138:139] op_sel_hi:[1,0]
	v_mul_f32_e32 v159, 0x3e16c740, v187
	v_cmp_neq_f32_e32 vcc, s81, v187
	s_nop 1
	v_cndmask_b32_e32 v159, 0, v159, vcc

; #define LAS __attribute__((address_space(3)))
; __device__ __forceinline__ float ex2(float x) { return __builtin_amdgcn_exp2f(x); }
; __device__ __forceinline__ f32x4 mfma16(bf16x8 a, bf16x8 b, f32x4 c) { return __builtin_amdgcn_mfma_f32_16x16x32_bf16(a, b, c, 0, 0, 0); }
;   __device__ __forceinline__ bf16_t* W() const { return (bf16_t*)(ws + WS_W); }
; template <int NT, int NKK, int NDT, int MODE, bool MASK> ...
;     ...
;   __builtin_amdgcn_s_setprio(1);
; #pragma unroll
;   for (int t = 0; t < 4; ++t)
; #pragma unroll
;     for (int kk = 0; kk < NKK; ++kk) {
;       const bf16x8 kf = *(LAS const bf16x8*)(Kl + (16 * t + r) * KSTR + (32 * kk + 8 * lg) * 2);
; #pragma unroll
;       for (int j = 0; j < NT; ++j) s[j][t] = mfma16(kf, qf[j][kk], kk == 0 ? (f32x4){0.f, 0.f, 0.f, 0.f} : s[j][t]);
;     }
;   __builtin_amdgcn_s_setprio(0);
;   bf16x8 pf[NT][2];
; #pragma unroll
;   for (int j = 0; j < NT; ++j) {
;     float mx = -INFINITY;
; #pragma unroll
;     for (int t = 0; t < 4; ++t)
; #pragma unroll
;       for (int i = 0; i < 4; ++i) {
;         if (MASK) { const int kp = kpos0 + 16 * t + 4 * lg + i; if (!mask_ok<MODE>(tq[j], kp, W)) s[j][t][i] = -INFINITY; }
;         mx = fmaxf(mx, s[j][t][i]);
;       }
;     mx = max_x16_x32(mx);
;     if (__any(mx > m[j] + 8.0f / c)) {
;       const float mnew = fmaxf(m[j], mx);
;       const float ms2 = (mnew == -INFINITY) ? 0.f : mnew;
;       const float alpha = ex2((m[j] - ms2) * c);
;       m[j] = mnew; l[j] *= alpha;
; #pragma unroll
;       for (int dt = 0; dt < NDT; ++dt) o[j][dt] *= alpha;
;     }
.LBB0_868:
	s_and_b64 vcc, exec, s[20:21]
	s_cbranch_vccz .LBB0_876
	v_add_f32_e32 v1, 0x4259535f, v220
	s_waitcnt lgkmcnt(10)
	v_mfma_f32_16x16x32_bf16 v[138:141], v[134:137], v[18:21], 0
	v_mfma_f32_16x16x32_bf16 v[134:137], v[134:137], v[10:13], 0
	s_waitcnt lgkmcnt(9)
	v_mfma_f32_16x16x32_bf16 v[138:141], v[130:133], v[2:5], v[138:141]
	v_mfma_f32_16x16x32_bf16 v[134:137], v[130:133], v[14:17], v[134:137]
	s_waitcnt lgkmcnt(8)
	v_mfma_f32_16x16x32_bf16 v[130:133], v[126:129], v[6:9], v[138:141]
	v_mfma_f32_16x16x32_bf16 v[126:129], v[126:129], v[22:25], v[134:137]
	s_waitcnt lgkmcnt(7)
	v_mfma_f32_16x16x32_bf16 v[134:137], v[122:125], v[18:21], 0
	v_mfma_f32_16x16x32_bf16 v[122:125], v[122:125], v[10:13], 0
	s_waitcnt lgkmcnt(6)
	v_mfma_f32_16x16x32_bf16 v[134:137], v[118:121], v[2:5], v[134:137]
	v_mfma_f32_16x16x32_bf16 v[118:121], v[118:121], v[14:17], v[122:125]
	s_waitcnt lgkmcnt(5)
	v_mfma_f32_16x16x32_bf16 v[134:137], v[114:117], v[6:9], v[134:137]
	v_mfma_f32_16x16x32_bf16 v[114:117], v[114:117], v[22:25], v[118:121]
	s_waitcnt lgkmcnt(4)
	v_mfma_f32_16x16x32_bf16 v[118:121], v[106:109], v[18:21], 0
	v_mfma_f32_16x16x32_bf16 v[106:109], v[106:109], v[10:13], 0
	s_waitcnt lgkmcnt(3)
	v_mfma_f32_16x16x32_bf16 v[118:121], v[98:101], v[2:5], v[118:121]
	v_mfma_f32_16x16x32_bf16 v[98:101], v[98:101], v[14:17], v[106:109]
	s_waitcnt lgkmcnt(1)
	v_mfma_f32_16x16x32_bf16 v[106:109], v[102:105], v[18:21], 0
	v_mfma_f32_16x16x32_bf16 v[102:105], v[102:105], v[10:13], 0
	s_waitcnt lgkmcnt(0)
	v_mfma_f32_16x16x32_bf16 v[106:109], v[94:97], v[2:5], v[106:109]
	v_mfma_f32_16x16x32_bf16 v[94:97], v[94:97], v[14:17], v[102:105]
	s_nop 4
	ds_read_b128 v[102:105], v201 offset:128
	v_mfma_f32_16x16x32_bf16 v[118:121], v[110:113], v[6:9], v[118:121]
	v_mfma_f32_16x16x32_bf16 v[98:101], v[110:113], v[22:25], v[98:101]
	s_waitcnt lgkmcnt(0)
	v_mfma_f32_16x16x32_bf16 v[94:97], v[102:105], v[22:25], v[94:97]
	v_mfma_f32_16x16x32_bf16 v[144:147], v[102:105], v[6:9], v[106:109]
	s_setprio 0
	v_add_u32_e32 v103, s69, v241
	v_subrev_u32_e32 v104, 63, v103
	v_subrev_u32_e32 v105, 61, v103
	v_mov_b32_e32 v102, s81
	v_cmp_gt_i32_e64 s[20:21], v104, v194
	v_cmp_lt_i32_e64 s[22:23], v104, v194
	v_cmp_le_i32_e32 vcc, v105, v194
	v_subrev_u32_e32 v106, 60, v103
	v_cndmask_b32_e64 v142, v130, v102, s[20:21]
	v_cndmask_b32_e64 v122, v200, v131, s[22:23]
	v_cndmask_b32_e32 v124, v200, v132, vcc
	v_cmp_le_i32_e32 vcc, v106, v194
	v_max3_f32 v102, v142, s81, v122
	v_subrev_u32_e32 v107, 47, v103
	v_cndmask_b32_e32 v123, v200, v133, vcc
	v_max3_f32 v108, v102, v124, v123
	v_mov_b32_e32 v102, s81
	v_cmp_gt_i32_e32 vcc, v107, v194
	v_subrev_u32_e32 v107, 46, v103
	v_subrev_u32_e32 v110, 44, v103
	v_cndmask_b32_e32 v125, v134, v102, vcc
	v_cmp_le_i32_e32 vcc, v107, v194
	v_subrev_u32_e32 v109, 31, v103
	v_subrev_u32_e32 v111, 30, v103
	v_cndmask_b32_e32 v131, v200, v135, vcc
	v_max3_f32 v102, v108, v125, v131
	v_subrev_u32_e32 v108, 45, v103
	v_cmp_le_i32_e32 vcc, v108, v194
	v_add_u32_e32 v113, -15, v103
	s_nop 0
	v_cndmask_b32_e32 v133, v200, v136, vcc
	v_cmp_le_i32_e32 vcc, v110, v194
	s_nop 1
	v_cndmask_b32_e32 v132, v200, v137, vcc
	v_max3_f32 v112, v102, v133, v132
	v_mov_b32_e32 v102, s81
	v_cmp_gt_i32_e32 vcc, v109, v194
	s_nop 1
	v_cndmask_b32_e32 v134, v118, v102, vcc
	v_cmp_le_i32_e32 vcc, v111, v194
	v_subrev_u32_e32 v118, 28, v103
	s_nop 0
	v_cndmask_b32_e32 v135, v200, v119, vcc
	v_max3_f32 v102, v112, v134, v135
	v_subrev_u32_e32 v112, 29, v103
	v_cmp_le_i32_e32 vcc, v112, v194
	v_add_u32_e32 v119, -14, v103
	s_nop 0
	v_cndmask_b32_e32 v137, v200, v120, vcc
	v_cmp_le_i32_e32 vcc, v118, v194
	s_nop 1
	v_cndmask_b32_e32 v136, v200, v121, vcc
	v_max3_f32 v120, v102, v137, v136
	v_mov_b32_e32 v102, s81
	v_cmp_gt_i32_e32 vcc, v113, v194
	v_add_u32_e32 v121, -12, v103
	s_nop 0
	v_cndmask_b32_e32 v138, v144, v102, vcc
	v_cmp_le_i32_e32 vcc, v119, v194
	s_nop 1
	v_cndmask_b32_e32 v139, v200, v145, vcc
	v_max3_f32 v102, v120, v138, v139
	v_add_u32_e32 v120, -13, v103
	v_cmp_le_i32_e32 vcc, v120, v194
	s_nop 1
	v_cndmask_b32_e32 v141, v200, v146, vcc
	v_cmp_le_i32_e32 vcc, v121, v194
	s_nop 1
	v_cndmask_b32_e32 v140, v200, v147, vcc
	v_max3_f32 v102, v102, v141, v140
	v_mov_b32_e32 v103, v102
	s_nop 1
	v_permlane16_swap_b32_e32 v102, v103
	v_max_f32_e32 v102, v102, v103
	v_mov_b32_e32 v103, v102
	s_nop 1
	v_permlane32_swap_b32_e32 v102, v103
	v_max_f32_e32 v102, v102, v103
	v_cmp_gt_f32_e32 vcc, v102, v1
	s_cbranch_vccz .LBB0_871
	v_max_f32_e32 v1, v102, v102
	v_max_f32_e32 v102, v220, v220
	v_max_f32_e32 v102, v102, v1
	v_cmp_neq_f32_e32 vcc, s81, v102
	v_mov_b32_e32 v103, v221
	s_nop 0
	v_cndmask_b32_e32 v1, 0, v102, vcc
	v_sub_f32_e32 v1, v220, v1
	v_mul_f32_e32 v1, 0x3e16c740, v1
	v_exp_f32_e32 v144, v1
	v_mov_b64_e32 v[220:221], v[102:103]
	v_mul_f32_e32 v218, v218, v144
	v_pk_mul_f32 v[92:93], v[92:93], v[144:145] op_sel_hi:[1,0]
	v_pk_mul_f32 v[90:91], v[90:91], v[144:145] op_sel_hi:[1,0]
	v_pk_mul_f32 v[88:89], v[88:89], v[144:145] op_sel_hi:[1,0]
	v_pk_mul_f32 v[86:87], v[86:87], v[144:145] op_sel_hi:[1,0]
	v_pk_mul_f32 v[76:77], v[76:77], v[144:145] op_sel_hi:[1,0]
	v_pk_mul_f32 v[74:75], v[74:75], v[144:145] op_sel_hi:[1,0]
	v_pk_mul_f32 v[68:69], v[68:69], v[144:145] op_sel_hi:[1,0]
	v_pk_mul_f32 v[66:67], v[66:67], v[144:145] op_sel_hi:[1,0]
	s_branch .LBB0_872

; #define LAS __attribute__((address_space(3)))
; #define LBAR() asm volatile("s_waitcnt lgkmcnt(0)\n\ts_barrier" ::: "memory")
; __device__ __forceinline__ f32x4 mfma16(bf16x8 a, bf16x8 b, f32x4 c) { return __builtin_amdgcn_mfma_f32_16x16x32_bf16(a, b, c, 0, 0, 0); }
;   __device__ __forceinline__ bf16_t* W() const { return (bf16_t*)(ws + WS_W); }
; template <int NT, int NKK, int NDT, int MODE, bool MASK> ...
;     ...
;   __builtin_amdgcn_s_setprio(1);
; #pragma unroll
;   for (int t = 0; t < 4; ++t)
; #pragma unroll
;     for (int kk = 0; kk < NKK; ++kk) {
;       const bf16x8 kf = *(LAS const bf16x8*)(Kl + (16 * t + r) * KSTR + (32 * kk + 8 * lg) * 2);
; #pragma unroll
;       for (int j = 0; j < NT; ++j) s[j][t] = mfma16(kf, qf[j][kk], kk == 0 ? (f32x4){0.f, 0.f, 0.f, 0.f} : s[j][t]);
;     }
;   __builtin_amdgcn_s_setprio(0);
;   bf16x8 pf[NT][2];
; #pragma unroll
;   for (int j = 0; j < NT; ++j) {
;     float mx = -INFINITY;
; #pragma unroll
;     for (int t = 0; t < 4; ++t)
; #pragma unroll
;       for (int i = 0; i < 4; ++i) {
;         if (MASK) { const int kp = kpos0 + 16 * t + 4 * lg + i; if (!mask_ok<MODE>(tq[j], kp, W)) s[j][t][i] = -INFINITY; }
;         mx = fmaxf(mx, s[j][t][i]);
;       }
;     mx = max_x16_x32(mx);
;     if (__any(mx > m[j] + 8.0f / c)) {
; template <int NT, int DQK, int DV, int MODE, int PD, class Src> ...
;     ...
;         LBAR();
;         const int lo = kbase + 64 * kc, hi = lo + 63;
;         bool rel = true, full = true;
;         if (MODE == MODE_CAUSAL) { rel = lo <= tq_max; full = hi <= tq_min; }
;         if (MODE == MODE_WINDOW) { rel = (lo <= tq_max) && (hi > tq_min - W); full = (hi <= tq_min) && (lo > tq_max - W); }
;         if (MODE == MODE_CMP) { rel = 16 * lo + 31 <= tq_max; full = 16 * hi + 31 <= tq_min; }
;         if (rel) {
;           if (NT <= 2) {
;             if (full) attn_chunk_wide<NT, DQK / 32, DV / 16, MODE, false>(o, m, l, qf, buf, KSTR, buf + KB, VSTR, lo, tq, c, W, lane);
;             else attn_chunk_wide<NT, DQK / 32, DV / 16, MODE, true>(o, m, l, qf, buf, KSTR, buf + KB, VSTR, lo, tq, c, W, lane);
.LBB0_941:
	s_waitcnt lgkmcnt(0)
	s_barrier
	s_add_i32 s8, s43, 0xffffff41
	s_cmp_gt_i32 s8, s40
	s_cbranch_scc1 .LBB0_970
	s_add_i32 s8, s43, 0xffffff80
	s_cmp_gt_i32 s8, s25
	s_setprio 1
	v_add_u32_e32 v1, s45, v236
	s_waitcnt lgkmcnt(0)
	v_add_u32_e32 v94, v1, v237
	ds_read_b128 v[134:137], v94
	ds_read_b128 v[130:133], v94 offset:64
	ds_read_b128 v[126:129], v94 offset:128
	ds_read_b128 v[122:125], v94 offset:3328
	ds_read_b128 v[118:121], v94 offset:3392
	ds_read_b128 v[114:117], v94 offset:3456
	ds_read_b128 v[106:109], v94 offset:6656
	ds_read_b128 v[98:101], v94 offset:6720
	v_add_u32_e32 v201, v1, v238
	ds_read_b128 v[110:113], v94 offset:6784
	ds_read_b128 v[102:105], v201
	ds_read_b128 v[94:97], v201 offset:64
	s_mov_b64 s[20:21], -1
	s_cbranch_scc1 .LBB0_961
	s_waitcnt lgkmcnt(10)
	v_mfma_f32_16x16x32_bf16 v[138:141], v[134:137], v[18:21], 0
	v_add_f32_e32 v1, 0x4259535f, v220
	ds_read_b128 v[146:149], v201 offset:128
	v_mov_b32_e32 v234, 0x260
	v_mfma_f32_16x16x32_bf16 v[142:145], v[134:137], v[10:13], 0
	s_waitcnt lgkmcnt(10)
	v_mfma_f32_16x16x32_bf16 v[138:141], v[130:133], v[2:5], v[138:141]
	v_mov_b64_e32 v[222:223], v[220:221]
	v_mfma_f32_16x16x32_bf16 v[142:145], v[130:133], v[14:17], v[142:145]
	v_mov_b64_e32 v[224:225], v[218:219]
	s_waitcnt lgkmcnt(9)
	v_mfma_f32_16x16x32_bf16 v[182:185], v[126:129], v[6:9], v[138:141]
	v_mfma_f32_16x16x32_bf16 v[166:169], v[126:129], v[22:25], v[142:145]
	v_mov_b32_e32 v187, v220
	s_waitcnt lgkmcnt(8)
	v_mfma_f32_16x16x32_bf16 v[138:141], v[122:125], v[18:21], 0
	v_add_f32_e32 v158, 0x4259535f, v221
	v_mfma_f32_16x16x32_bf16 v[142:145], v[122:125], v[10:13], 0
	v_mul_f32_e32 v159, 0x3e16c740, v220
	s_waitcnt lgkmcnt(7)
	v_mfma_f32_16x16x32_bf16 v[138:141], v[118:121], v[2:5], v[138:141]
	v_cmp_neq_f32_e64 s[22:23], s81, v220
	v_mfma_f32_16x16x32_bf16 v[142:145], v[118:121], v[14:17], v[142:145]
	s_waitcnt lgkmcnt(6)
	v_mfma_f32_16x16x32_bf16 v[178:181], v[114:117], v[6:9], v[138:141]
	v_mfma_f32_16x16x32_bf16 v[154:157], v[114:117], v[22:25], v[142:145]
	v_cndmask_b32_e64 v159, 0, v159, s[22:23]
	s_waitcnt lgkmcnt(5)
	v_mfma_f32_16x16x32_bf16 v[138:141], v[106:109], v[18:21], 0
	v_mul_f32_e32 v160, 0x3e16c740, v221
	v_mfma_f32_16x16x32_bf16 v[142:145], v[106:109], v[10:13], 0
	v_cmp_neq_f32_e64 s[22:23], s81, v221
	v_max3_f32 v188, v182, s81, v183
	s_waitcnt lgkmcnt(4)
	v_mfma_f32_16x16x32_bf16 v[138:141], v[98:101], v[2:5], v[138:141]
	v_max3_f32 v188, v188, v184, v185
	v_mfma_f32_16x16x32_bf16 v[142:145], v[98:101], v[14:17], v[142:145]
	v_max3_f32 v189, v166, s81, v167
	s_waitcnt lgkmcnt(3)
	v_mfma_f32_16x16x32_bf16 v[174:177], v[110:113], v[6:9], v[138:141]
	v_cndmask_b32_e64 v160, 0, v160, s[22:23]
	v_max3_f32 v189, v189, v168, v169
	v_mfma_f32_16x16x32_bf16 v[150:153], v[110:113], v[22:25], v[142:145]
	s_waitcnt lgkmcnt(2)
	v_mfma_f32_16x16x32_bf16 v[138:141], v[102:105], v[18:21], 0
	v_mfma_f32_16x16x32_bf16 v[142:145], v[102:105], v[10:13], 0
	v_max3_f32 v188, v188, v178, v179
	s_waitcnt lgkmcnt(1)
	v_mfma_f32_16x16x32_bf16 v[138:141], v[94:97], v[2:5], v[138:141]
	v_max3_f32 v188, v188, v180, v181
	v_mfma_f32_16x16x32_bf16 v[142:145], v[94:97], v[14:17], v[142:145]
	v_max3_f32 v189, v189, v154, v155
	s_waitcnt lgkmcnt(0)
	v_mfma_f32_16x16x32_bf16 v[170:173], v[146:149], v[6:9], v[138:141]
	v_max3_f32 v189, v189, v156, v157
	v_mfma_f32_16x16x32_bf16 v[142:145], v[146:149], v[22:25], v[142:145]
	s_setprio 0
	s_nop 3
	v_max3_f32 v138, v188, v174, v175
	v_max3_f32 v138, v138, v176, v177
	v_max3_f32 v138, v138, v170, v171
	v_max3_f32 v138, v138, v172, v173
	v_mov_b32_e32 v139, v138
	s_nop 1
	v_permlane16_swap_b32_e32 v138, v139
	v_max_f32_e32 v138, v138, v139
	v_mov_b32_e32 v139, v138
	s_nop 1
	v_permlane32_swap_b32_e32 v138, v139
	v_max_f32_e32 v186, v138, v139
	v_cmp_gt_f32_e32 vcc, v186, v1
	s_cbranch_vccz .LBB0_945
	v_max_f32_e32 v138, v186, v186
	v_max_f32_e32 v139, v220, v220
	v_max_f32_e32 v222, v139, v138
	v_cmp_neq_f32_e32 vcc, s81, v222
	v_mov_b32_e32 v223, v221
	v_mov_b32_e32 v225, v219
	v_cndmask_b32_e32 v138, 0, v222, vcc
	v_sub_f32_e32 v138, v220, v138
	v_mul_f32_e32 v138, 0x3e16c740, v138
	v_exp_f32_e32 v138, v138
	v_mov_b32_e32 v187, v222
	v_mul_f32_e32 v224, v218, v138
	v_pk_mul_f32 v[92:93], v[92:93], v[138:139] op_sel_hi:[1,0]
	v_pk_mul_f32 v[90:91], v[90:91], v[138:139] op_sel_hi:[1,0]
	v_pk_mul_f32 v[88:89], v[88:89], v[138:139] op_sel_hi:[1,0]
	v_pk_mul_f32 v[86:87], v[86:87], v[138:139] op_sel_hi:[1,0]
	v_pk_mul_f32 v[76:77], v[76:77], v[138:139] op_sel_hi:[1,0]
	v_pk_mul_f32 v[74:75], v[74:75], v[138:139] op_sel_hi:[1,0]
	v_pk_mul_f32 v[68:69], v[68:69], v[138:139] op_sel_hi:[1,0]
	v_pk_mul_f32 v[66:67], v[66:67], v[138:139] op_sel_hi:[1,0]
	v_mul_f32_e32 v159, 0x3e16c740, v187
	v_cmp_neq_f32_e32 vcc, s81, v187
	s_nop 1
	v_cndmask_b32_e32 v159, 0, v159, vcc

; #define LAS __attribute__((address_space(3)))
; __device__ __forceinline__ float ex2(float x) { return __builtin_amdgcn_exp2f(x); }
; __device__ __forceinline__ f32x4 mfma16(bf16x8 a, bf16x8 b, f32x4 c) { return __builtin_amdgcn_mfma_f32_16x16x32_bf16(a, b, c, 0, 0, 0); }
;   __device__ __forceinline__ bf16_t* W() const { return (bf16_t*)(ws + WS_W); }
; template <int NT, int NKK, int NDT, int MODE, bool MASK> ...
;     ...
;   __builtin_amdgcn_s_setprio(1);
; #pragma unroll
;   for (int t = 0; t < 4; ++t)
; #pragma unroll
;     for (int kk = 0; kk < NKK; ++kk) {
;       const bf16x8 kf = *(LAS const bf16x8*)(Kl + (16 * t + r) * KSTR + (32 * kk + 8 * lg) * 2);
; #pragma unroll
;       for (int j = 0; j < NT; ++j) s[j][t] = mfma16(kf, qf[j][kk], kk == 0 ? (f32x4){0.f, 0.f, 0.f, 0.f} : s[j][t]);
;     }
;   __builtin_amdgcn_s_setprio(0);
;   bf16x8 pf[NT][2];
; #pragma unroll
;   for (int j = 0; j < NT; ++j) {
;     float mx = -INFINITY;
; #pragma unroll
;     for (int t = 0; t < 4; ++t)
; #pragma unroll
;       for (int i = 0; i < 4; ++i) {
;         if (MASK) { const int kp = kpos0 + 16 * t + 4 * lg + i; if (!mask_ok<MODE>(tq[j], kp, W)) s[j][t][i] = -INFINITY; }
;         mx = fmaxf(mx, s[j][t][i]);
;       }
;     mx = max_x16_x32(mx);
;     if (__any(mx > m[j] + 8.0f / c)) {
;       const float mnew = fmaxf(m[j], mx);
;       const float ms2 = (mnew == -INFINITY) ? 0.f : mnew;
;       const float alpha = ex2((m[j] - ms2) * c);
;       m[j] = mnew; l[j] *= alpha;
; #pragma unroll
;       for (int dt = 0; dt < NDT; ++dt) o[j][dt] *= alpha;
;     }
.LBB0_961:
	s_and_b64 vcc, exec, s[20:21]
	s_cbranch_vccz .LBB0_969
	v_add_f32_e32 v1, 0x4259535f, v220
	s_waitcnt lgkmcnt(10)
	v_mfma_f32_16x16x32_bf16 v[138:141], v[134:137], v[18:21], 0
	v_mfma_f32_16x16x32_bf16 v[134:137], v[134:137], v[10:13], 0
	s_waitcnt lgkmcnt(9)
	v_mfma_f32_16x16x32_bf16 v[138:141], v[130:133], v[2:5], v[138:141]
	v_mfma_f32_16x16x32_bf16 v[134:137], v[130:133], v[14:17], v[134:137]
	s_waitcnt lgkmcnt(8)
	v_mfma_f32_16x16x32_bf16 v[130:133], v[126:129], v[6:9], v[138:141]
	v_mfma_f32_16x16x32_bf16 v[126:129], v[126:129], v[22:25], v[134:137]
	s_waitcnt lgkmcnt(7)
	v_mfma_f32_16x16x32_bf16 v[134:137], v[122:125], v[18:21], 0
	v_mfma_f32_16x16x32_bf16 v[122:125], v[122:125], v[10:13], 0
	s_waitcnt lgkmcnt(6)
	v_mfma_f32_16x16x32_bf16 v[134:137], v[118:121], v[2:5], v[134:137]
	v_mfma_f32_16x16x32_bf16 v[118:121], v[118:121], v[14:17], v[122:125]
	s_waitcnt lgkmcnt(5)
	v_mfma_f32_16x16x32_bf16 v[134:137], v[114:117], v[6:9], v[134:137]
	v_mfma_f32_16x16x32_bf16 v[114:117], v[114:117], v[22:25], v[118:121]
	s_waitcnt lgkmcnt(4)
	v_mfma_f32_16x16x32_bf16 v[118:121], v[106:109], v[18:21], 0
	v_mfma_f32_16x16x32_bf16 v[106:109], v[106:109], v[10:13], 0
	s_waitcnt lgkmcnt(3)
	v_mfma_f32_16x16x32_bf16 v[118:121], v[98:101], v[2:5], v[118:121]
	v_mfma_f32_16x16x32_bf16 v[98:101], v[98:101], v[14:17], v[106:109]
	s_waitcnt lgkmcnt(1)
	v_mfma_f32_16x16x32_bf16 v[106:109], v[102:105], v[18:21], 0
	v_mfma_f32_16x16x32_bf16 v[102:105], v[102:105], v[10:13], 0
	s_waitcnt lgkmcnt(0)
	v_mfma_f32_16x16x32_bf16 v[106:109], v[94:97], v[2:5], v[106:109]
	v_mfma_f32_16x16x32_bf16 v[94:97], v[94:97], v[14:17], v[102:105]
	s_nop 4
	ds_read_b128 v[102:105], v201 offset:128
	v_mfma_f32_16x16x32_bf16 v[118:121], v[110:113], v[6:9], v[118:121]
	v_mfma_f32_16x16x32_bf16 v[98:101], v[110:113], v[22:25], v[98:101]
	s_waitcnt lgkmcnt(0)
	v_mfma_f32_16x16x32_bf16 v[94:97], v[102:105], v[22:25], v[94:97]
	v_mfma_f32_16x16x32_bf16 v[144:147], v[102:105], v[6:9], v[106:109]
	s_setprio 0
	v_add_u32_e32 v103, s43, v241
	v_add_u32_e32 v104, 0xffffff41, v103
	v_add_u32_e32 v105, 0xffffff43, v103
	v_mov_b32_e32 v102, s81
	v_cmp_gt_i32_e64 s[20:21], v104, v194
	v_cmp_lt_i32_e64 s[22:23], v104, v194
	v_cmp_le_i32_e32 vcc, v105, v194
	v_add_u32_e32 v106, 0xffffff44, v103
	v_cndmask_b32_e64 v142, v130, v102, s[20:21]
	v_cndmask_b32_e64 v122, v200, v131, s[22:23]
	v_cndmask_b32_e32 v124, v200, v132, vcc
	v_cmp_le_i32_e32 vcc, v106, v194
	v_max3_f32 v102, v142, s81, v122
	v_add_u32_e32 v107, 0xffffff51, v103
	v_cndmask_b32_e32 v123, v200, v133, vcc
	v_max3_f32 v108, v102, v124, v123
	v_mov_b32_e32 v102, s81
	v_cmp_gt_i32_e32 vcc, v107, v194
	v_add_u32_e32 v107, 0xffffff52, v103
	v_add_u32_e32 v110, 0xffffff54, v103
	v_cndmask_b32_e32 v125, v134, v102, vcc
	v_cmp_le_i32_e32 vcc, v107, v194
	v_add_u32_e32 v109, 0xffffff61, v103
	v_add_u32_e32 v111, 0xffffff62, v103
	v_cndmask_b32_e32 v131, v200, v135, vcc
	v_max3_f32 v102, v108, v125, v131
	v_add_u32_e32 v108, 0xffffff53, v103
	v_cmp_le_i32_e32 vcc, v108, v194
	v_add_u32_e32 v113, 0xffffff71, v103
	s_nop 0
	v_cndmask_b32_e32 v133, v200, v136, vcc
	v_cmp_le_i32_e32 vcc, v110, v194
	s_nop 1
	v_cndmask_b32_e32 v132, v200, v137, vcc
	v_max3_f32 v112, v102, v133, v132
	v_mov_b32_e32 v102, s81
	v_cmp_gt_i32_e32 vcc, v109, v194
	s_nop 1
	v_cndmask_b32_e32 v134, v118, v102, vcc
	v_cmp_le_i32_e32 vcc, v111, v194
	v_add_u32_e32 v118, 0xffffff64, v103
	s_nop 0
	v_cndmask_b32_e32 v135, v200, v119, vcc
	v_max3_f32 v102, v112, v134, v135
	v_add_u32_e32 v112, 0xffffff63, v103
	v_cmp_le_i32_e32 vcc, v112, v194
	v_add_u32_e32 v119, 0xffffff72, v103
	s_nop 0
	v_cndmask_b32_e32 v137, v200, v120, vcc
	v_cmp_le_i32_e32 vcc, v118, v194
	s_nop 1
	v_cndmask_b32_e32 v136, v200, v121, vcc
	v_max3_f32 v120, v102, v137, v136
	v_mov_b32_e32 v102, s81
	v_cmp_gt_i32_e32 vcc, v113, v194
	v_add_u32_e32 v121, 0xffffff74, v103
	s_nop 0
	v_cndmask_b32_e32 v138, v144, v102, vcc
	v_cmp_le_i32_e32 vcc, v119, v194
	s_nop 1
	v_cndmask_b32_e32 v139, v200, v145, vcc
	v_max3_f32 v102, v120, v138, v139
	v_add_u32_e32 v120, 0xffffff73, v103
	v_cmp_le_i32_e32 vcc, v120, v194
	s_nop 1
	v_cndmask_b32_e32 v141, v200, v146, vcc
	v_cmp_le_i32_e32 vcc, v121, v194
	s_nop 1
	v_cndmask_b32_e32 v140, v200, v147, vcc
	v_max3_f32 v102, v102, v141, v140
	v_mov_b32_e32 v103, v102
	s_nop 1
	v_permlane16_swap_b32_e32 v102, v103
	v_max_f32_e32 v102, v102, v103
	v_mov_b32_e32 v103, v102
	s_nop 1
	v_permlane32_swap_b32_e32 v102, v103
	v_max_f32_e32 v102, v102, v103
	v_cmp_gt_f32_e32 vcc, v102, v1
	s_cbranch_vccz .LBB0_964
	v_max_f32_e32 v1, v102, v102
	v_max_f32_e32 v102, v220, v220
	v_max_f32_e32 v102, v102, v1
	v_cmp_neq_f32_e32 vcc, s81, v102
	v_mov_b32_e32 v103, v221
	s_nop 0
	v_cndmask_b32_e32 v1, 0, v102, vcc
	v_sub_f32_e32 v1, v220, v1
	v_mul_f32_e32 v1, 0x3e16c740, v1
	v_exp_f32_e32 v144, v1
	v_mov_b64_e32 v[220:221], v[102:103]
	v_mul_f32_e32 v218, v218, v144
	v_pk_mul_f32 v[92:93], v[92:93], v[144:145] op_sel_hi:[1,0]
	v_pk_mul_f32 v[90:91], v[90:91], v[144:145] op_sel_hi:[1,0]
	v_pk_mul_f32 v[88:89], v[88:89], v[144:145] op_sel_hi:[1,0]
	v_pk_mul_f32 v[86:87], v[86:87], v[144:145] op_sel_hi:[1,0]
	v_pk_mul_f32 v[76:77], v[76:77], v[144:145] op_sel_hi:[1,0]
	v_pk_mul_f32 v[74:75], v[74:75], v[144:145] op_sel_hi:[1,0]
	v_pk_mul_f32 v[68:69], v[68:69], v[144:145] op_sel_hi:[1,0]
	v_pk_mul_f32 v[66:67], v[66:67], v[144:145] op_sel_hi:[1,0]
	s_branch .LBB0_965

; #define LAS __attribute__((address_space(3)))
; #define LBAR() asm volatile("s_waitcnt lgkmcnt(0)\n\ts_barrier" ::: "memory")
; __device__ __forceinline__ f32x4 mfma16(bf16x8 a, bf16x8 b, f32x4 c) { return __builtin_amdgcn_mfma_f32_16x16x32_bf16(a, b, c, 0, 0, 0); }
;   __device__ __forceinline__ bf16_t* W() const { return (bf16_t*)(ws + WS_W); }
; template <int NT, int NKK, int NDT, int MODE, bool MASK> ...
;     ...
;   __builtin_amdgcn_s_setprio(1);
; #pragma unroll
;   for (int t = 0; t < 4; ++t)
; #pragma unroll
;     for (int kk = 0; kk < NKK; ++kk) {
;       const bf16x8 kf = *(LAS const bf16x8*)(Kl + (16 * t + r) * KSTR + (32 * kk + 8 * lg) * 2);
; #pragma unroll
;       for (int j = 0; j < NT; ++j) s[j][t] = mfma16(kf, qf[j][kk], kk == 0 ? (f32x4){0.f, 0.f, 0.f, 0.f} : s[j][t]);
;     }
;   __builtin_amdgcn_s_setprio(0);
;   bf16x8 pf[NT][2];
; #pragma unroll
;   for (int j = 0; j < NT; ++j) {
;     float mx = -INFINITY;
; #pragma unroll
;     for (int t = 0; t < 4; ++t)
; #pragma unroll
;       for (int i = 0; i < 4; ++i) {
;         if (MASK) { const int kp = kpos0 + 16 * t + 4 * lg + i; if (!mask_ok<MODE>(tq[j], kp, W)) s[j][t][i] = -INFINITY; }
;         mx = fmaxf(mx, s[j][t][i]);
;       }
;     mx = max_x16_x32(mx);
;     if (__any(mx > m[j] + 8.0f / c)) {
; template <int NT, int DQK, int DV, int MODE, int PD, class Src> ...
;     ...
;         LBAR();
;         const int lo = kbase + 64 * kc, hi = lo + 63;
;         bool rel = true, full = true;
;         if (MODE == MODE_CAUSAL) { rel = lo <= tq_max; full = hi <= tq_min; }
;         if (MODE == MODE_WINDOW) { rel = (lo <= tq_max) && (hi > tq_min - W); full = (hi <= tq_min) && (lo > tq_max - W); }
;         if (MODE == MODE_CMP) { rel = 16 * lo + 31 <= tq_max; full = 16 * hi + 31 <= tq_min; }
;         if (rel) {
;           if (NT <= 2) {
;             if (full) attn_chunk_wide<NT, DQK / 32, DV / 16, MODE, false>(o, m, l, qf, buf, KSTR, buf + KB, VSTR, lo, tq, c, W, lane);
;             else attn_chunk_wide<NT, DQK / 32, DV / 16, MODE, true>(o, m, l, qf, buf, KSTR, buf + KB, VSTR, lo, tq, c, W, lane);
.LBB0_983:
	s_waitcnt lgkmcnt(0)
	s_barrier
	s_add_i32 s8, s43, 0xffffff81
	s_cmp_gt_i32 s8, s40
	s_cbranch_scc1 .LBB0_1010
	s_sub_i32 s8, s43, 64
	s_cmp_gt_i32 s8, s25
	s_setprio 1
	v_add_u32_e32 v1, s59, v236
	s_waitcnt lgkmcnt(0)
	v_add_u32_e32 v94, v1, v237
	ds_read_b128 v[134:137], v94
	ds_read_b128 v[130:133], v94 offset:64
	ds_read_b128 v[126:129], v94 offset:128
	ds_read_b128 v[122:125], v94 offset:3328
	ds_read_b128 v[118:121], v94 offset:3392
	ds_read_b128 v[114:117], v94 offset:3456
	ds_read_b128 v[106:109], v94 offset:6656
	ds_read_b128 v[98:101], v94 offset:6720
	v_add_u32_e32 v201, v1, v238
	ds_read_b128 v[110:113], v94 offset:6784
	ds_read_b128 v[102:105], v201
	ds_read_b128 v[94:97], v201 offset:64
	s_mov_b64 s[20:21], -1
	s_cbranch_scc1 .LBB0_1001
	s_waitcnt lgkmcnt(10)
	v_mfma_f32_16x16x32_bf16 v[138:141], v[134:137], v[18:21], 0
	v_add_f32_e32 v1, 0x4259535f, v220
	ds_read_b128 v[146:149], v201 offset:128
	v_mov_b32_e32 v234, 0x260
	v_mfma_f32_16x16x32_bf16 v[142:145], v[134:137], v[10:13], 0
	s_waitcnt lgkmcnt(10)
	v_mfma_f32_16x16x32_bf16 v[138:141], v[130:133], v[2:5], v[138:141]
	v_mov_b64_e32 v[222:223], v[220:221]
	v_mfma_f32_16x16x32_bf16 v[142:145], v[130:133], v[14:17], v[142:145]
	v_mov_b64_e32 v[224:225], v[218:219]
	s_waitcnt lgkmcnt(9)
	v_mfma_f32_16x16x32_bf16 v[182:185], v[126:129], v[6:9], v[138:141]
	v_mfma_f32_16x16x32_bf16 v[166:169], v[126:129], v[22:25], v[142:145]
	v_mov_b32_e32 v187, v220
	s_waitcnt lgkmcnt(8)
	v_mfma_f32_16x16x32_bf16 v[138:141], v[122:125], v[18:21], 0
	v_add_f32_e32 v158, 0x4259535f, v221
	v_mfma_f32_16x16x32_bf16 v[142:145], v[122:125], v[10:13], 0
	v_mul_f32_e32 v159, 0x3e16c740, v220
	s_waitcnt lgkmcnt(7)
	v_mfma_f32_16x16x32_bf16 v[138:141], v[118:121], v[2:5], v[138:141]
	v_cmp_neq_f32_e64 s[22:23], s81, v220
	v_mfma_f32_16x16x32_bf16 v[142:145], v[118:121], v[14:17], v[142:145]
	s_waitcnt lgkmcnt(6)
	v_mfma_f32_16x16x32_bf16 v[178:181], v[114:117], v[6:9], v[138:141]
	v_mfma_f32_16x16x32_bf16 v[154:157], v[114:117], v[22:25], v[142:145]
	v_cndmask_b32_e64 v159, 0, v159, s[22:23]
	s_waitcnt lgkmcnt(5)
	v_mfma_f32_16x16x32_bf16 v[138:141], v[106:109], v[18:21], 0
	v_mul_f32_e32 v160, 0x3e16c740, v221
	v_mfma_f32_16x16x32_bf16 v[142:145], v[106:109], v[10:13], 0
	v_cmp_neq_f32_e64 s[22:23], s81, v221
	v_max3_f32 v188, v182, s81, v183
	s_waitcnt lgkmcnt(4)
	v_mfma_f32_16x16x32_bf16 v[138:141], v[98:101], v[2:5], v[138:141]
	v_max3_f32 v188, v188, v184, v185
	v_mfma_f32_16x16x32_bf16 v[142:145], v[98:101], v[14:17], v[142:145]
	v_max3_f32 v189, v166, s81, v167
	s_waitcnt lgkmcnt(3)
	v_mfma_f32_16x16x32_bf16 v[174:177], v[110:113], v[6:9], v[138:141]
	v_cndmask_b32_e64 v160, 0, v160, s[22:23]
	v_max3_f32 v189, v189, v168, v169
	v_mfma_f32_16x16x32_bf16 v[150:153], v[110:113], v[22:25], v[142:145]
	s_waitcnt lgkmcnt(2)
	v_mfma_f32_16x16x32_bf16 v[138:141], v[102:105], v[18:21], 0
	v_mfma_f32_16x16x32_bf16 v[142:145], v[102:105], v[10:13], 0
	v_max3_f32 v188, v188, v178, v179
	s_waitcnt lgkmcnt(1)
	v_mfma_f32_16x16x32_bf16 v[138:141], v[94:97], v[2:5], v[138:141]
	v_max3_f32 v188, v188, v180, v181
	v_mfma_f32_16x16x32_bf16 v[142:145], v[94:97], v[14:17], v[142:145]
	v_max3_f32 v189, v189, v154, v155
	s_waitcnt lgkmcnt(0)
	v_mfma_f32_16x16x32_bf16 v[170:173], v[146:149], v[6:9], v[138:141]
	v_max3_f32 v189, v189, v156, v157
	v_mfma_f32_16x16x32_bf16 v[142:145], v[146:149], v[22:25], v[142:145]
	s_setprio 0
	s_nop 3
	v_max3_f32 v138, v188, v174, v175
	v_max3_f32 v138, v138, v176, v177
	v_max3_f32 v138, v138, v170, v171
	v_max3_f32 v138, v138, v172, v173
	v_mov_b32_e32 v139, v138
	s_nop 1
	v_permlane16_swap_b32_e32 v138, v139
	v_max_f32_e32 v138, v138, v139
	v_mov_b32_e32 v139, v138
	s_nop 1
	v_permlane32_swap_b32_e32 v138, v139
	v_max_f32_e32 v186, v138, v139
	v_cmp_gt_f32_e32 vcc, v186, v1
	s_cbranch_vccz .LBB0_987
	v_max_f32_e32 v138, v186, v186
	v_max_f32_e32 v139, v220, v220
	v_max_f32_e32 v222, v139, v138
	v_cmp_neq_f32_e32 vcc, s81, v222
	v_mov_b32_e32 v223, v221
	v_mov_b32_e32 v225, v219
	v_cndmask_b32_e32 v138, 0, v222, vcc
	v_sub_f32_e32 v138, v220, v138
	v_mul_f32_e32 v138, 0x3e16c740, v138
	v_exp_f32_e32 v138, v138
	v_mov_b32_e32 v187, v222
	v_mul_f32_e32 v224, v218, v138
	v_pk_mul_f32 v[92:93], v[92:93], v[138:139] op_sel_hi:[1,0]
	v_pk_mul_f32 v[90:91], v[90:91], v[138:139] op_sel_hi:[1,0]
	v_pk_mul_f32 v[88:89], v[88:89], v[138:139] op_sel_hi:[1,0]
	v_pk_mul_f32 v[86:87], v[86:87], v[138:139] op_sel_hi:[1,0]
	v_pk_mul_f32 v[76:77], v[76:77], v[138:139] op_sel_hi:[1,0]
	v_pk_mul_f32 v[74:75], v[74:75], v[138:139] op_sel_hi:[1,0]
	v_pk_mul_f32 v[68:69], v[68:69], v[138:139] op_sel_hi:[1,0]
	v_pk_mul_f32 v[66:67], v[66:67], v[138:139] op_sel_hi:[1,0]
	v_mul_f32_e32 v159, 0x3e16c740, v187
	v_cmp_neq_f32_e32 vcc, s81, v187
	s_nop 1
	v_cndmask_b32_e32 v159, 0, v159, vcc

; #define LAS __attribute__((address_space(3)))
; __device__ __forceinline__ float ex2(float x) { return __builtin_amdgcn_exp2f(x); }
; __device__ __forceinline__ f32x4 mfma16(bf16x8 a, bf16x8 b, f32x4 c) { return __builtin_amdgcn_mfma_f32_16x16x32_bf16(a, b, c, 0, 0, 0); }
;   __device__ __forceinline__ bf16_t* W() const { return (bf16_t*)(ws + WS_W); }
; template <int NT, int NKK, int NDT, int MODE, bool MASK> ...
;     ...
;   __builtin_amdgcn_s_setprio(1);
; #pragma unroll
;   for (int t = 0; t < 4; ++t)
; #pragma unroll
;     for (int kk = 0; kk < NKK; ++kk) {
;       const bf16x8 kf = *(LAS const bf16x8*)(Kl + (16 * t + r) * KSTR + (32 * kk + 8 * lg) * 2);
; #pragma unroll
;       for (int j = 0; j < NT; ++j) s[j][t] = mfma16(kf, qf[j][kk], kk == 0 ? (f32x4){0.f, 0.f, 0.f, 0.f} : s[j][t]);
;     }
;   __builtin_amdgcn_s_setprio(0);
;   bf16x8 pf[NT][2];
; #pragma unroll
;   for (int j = 0; j < NT; ++j) {
;     float mx = -INFINITY;
; #pragma unroll
;     for (int t = 0; t < 4; ++t)
; #pragma unroll
;       for (int i = 0; i < 4; ++i) {
;         if (MASK) { const int kp = kpos0 + 16 * t + 4 * lg + i; if (!mask_ok<MODE>(tq[j], kp, W)) s[j][t][i] = -INFINITY; }
;         mx = fmaxf(mx, s[j][t][i]);
;       }
;     mx = max_x16_x32(mx);
;     if (__any(mx > m[j] + 8.0f / c)) {
;       const float mnew = fmaxf(m[j], mx);
;       const float ms2 = (mnew == -INFINITY) ? 0.f : mnew;
;       const float alpha = ex2((m[j] - ms2) * c);
;       m[j] = mnew; l[j] *= alpha;
; #pragma unroll
;       for (int dt = 0; dt < NDT; ++dt) o[j][dt] *= alpha;
;     }
.LBB0_1001:
	s_and_b64 vcc, exec, s[20:21]
	s_cbranch_vccz .LBB0_1009
	v_add_f32_e32 v1, 0x4259535f, v220
	s_waitcnt lgkmcnt(10)
	v_mfma_f32_16x16x32_bf16 v[138:141], v[134:137], v[18:21], 0
	v_mfma_f32_16x16x32_bf16 v[134:137], v[134:137], v[10:13], 0
	s_waitcnt lgkmcnt(9)
	v_mfma_f32_16x16x32_bf16 v[138:141], v[130:133], v[2:5], v[138:141]
	v_mfma_f32_16x16x32_bf16 v[134:137], v[130:133], v[14:17], v[134:137]
	s_waitcnt lgkmcnt(8)
	v_mfma_f32_16x16x32_bf16 v[130:133], v[126:129], v[6:9], v[138:141]
	v_mfma_f32_16x16x32_bf16 v[126:129], v[126:129], v[22:25], v[134:137]
	s_waitcnt lgkmcnt(7)
	v_mfma_f32_16x16x32_bf16 v[134:137], v[122:125], v[18:21], 0
	v_mfma_f32_16x16x32_bf16 v[122:125], v[122:125], v[10:13], 0
	s_waitcnt lgkmcnt(6)
	v_mfma_f32_16x16x32_bf16 v[134:137], v[118:121], v[2:5], v[134:137]
	v_mfma_f32_16x16x32_bf16 v[118:121], v[118:121], v[14:17], v[122:125]
	s_waitcnt lgkmcnt(5)
	v_mfma_f32_16x16x32_bf16 v[134:137], v[114:117], v[6:9], v[134:137]
	v_mfma_f32_16x16x32_bf16 v[114:117], v[114:117], v[22:25], v[118:121]
	s_waitcnt lgkmcnt(4)
	v_mfma_f32_16x16x32_bf16 v[118:121], v[106:109], v[18:21], 0
	v_mfma_f32_16x16x32_bf16 v[106:109], v[106:109], v[10:13], 0
	s_waitcnt lgkmcnt(3)
	v_mfma_f32_16x16x32_bf16 v[118:121], v[98:101], v[2:5], v[118:121]
	v_mfma_f32_16x16x32_bf16 v[98:101], v[98:101], v[14:17], v[106:109]
	s_waitcnt lgkmcnt(1)
	v_mfma_f32_16x16x32_bf16 v[106:109], v[102:105], v[18:21], 0
	v_mfma_f32_16x16x32_bf16 v[102:105], v[102:105], v[10:13], 0
	s_waitcnt lgkmcnt(0)
	v_mfma_f32_16x16x32_bf16 v[106:109], v[94:97], v[2:5], v[106:109]
	v_mfma_f32_16x16x32_bf16 v[94:97], v[94:97], v[14:17], v[102:105]
	s_nop 4
	ds_read_b128 v[102:105], v201 offset:128
	v_mfma_f32_16x16x32_bf16 v[118:121], v[110:113], v[6:9], v[118:121]
	v_mfma_f32_16x16x32_bf16 v[98:101], v[110:113], v[22:25], v[98:101]
	s_waitcnt lgkmcnt(0)
	v_mfma_f32_16x16x32_bf16 v[94:97], v[102:105], v[22:25], v[94:97]
	v_mfma_f32_16x16x32_bf16 v[144:147], v[102:105], v[6:9], v[106:109]
	s_setprio 0
	v_add_u32_e32 v103, s43, v241
	v_add_u32_e32 v104, 0xffffff81, v103
	v_add_u32_e32 v105, 0xffffff83, v103
	v_mov_b32_e32 v102, s81
	v_cmp_gt_i32_e64 s[20:21], v104, v194
	v_cmp_lt_i32_e64 s[22:23], v104, v194
	v_cmp_le_i32_e32 vcc, v105, v194
	v_add_u32_e32 v106, 0xffffff84, v103
	v_cndmask_b32_e64 v142, v130, v102, s[20:21]
	v_cndmask_b32_e64 v122, v200, v131, s[22:23]
	v_cndmask_b32_e32 v124, v200, v132, vcc
	v_cmp_le_i32_e32 vcc, v106, v194
	v_max3_f32 v102, v142, s81, v122
	v_add_u32_e32 v107, 0xffffff91, v103
	v_cndmask_b32_e32 v123, v200, v133, vcc
	v_max3_f32 v108, v102, v124, v123
	v_mov_b32_e32 v102, s81
	v_cmp_gt_i32_e32 vcc, v107, v194
	v_add_u32_e32 v107, 0xffffff92, v103
	v_add_u32_e32 v110, 0xffffff94, v103
	v_cndmask_b32_e32 v125, v134, v102, vcc
	v_cmp_le_i32_e32 vcc, v107, v194
	v_add_u32_e32 v109, 0xffffffa1, v103
	v_add_u32_e32 v111, 0xffffffa2, v103
	v_cndmask_b32_e32 v131, v200, v135, vcc
	v_max3_f32 v102, v108, v125, v131
	v_add_u32_e32 v108, 0xffffff93, v103
	v_cmp_le_i32_e32 vcc, v108, v194
	v_add_u32_e32 v113, 0xffffffb1, v103
	s_nop 0
	v_cndmask_b32_e32 v133, v200, v136, vcc
	v_cmp_le_i32_e32 vcc, v110, v194
	s_nop 1
	v_cndmask_b32_e32 v132, v200, v137, vcc
	v_max3_f32 v112, v102, v133, v132
	v_mov_b32_e32 v102, s81
	v_cmp_gt_i32_e32 vcc, v109, v194
	s_nop 1
	v_cndmask_b32_e32 v134, v118, v102, vcc
	v_cmp_le_i32_e32 vcc, v111, v194
	v_add_u32_e32 v118, 0xffffffa4, v103
	s_nop 0
	v_cndmask_b32_e32 v135, v200, v119, vcc
	v_max3_f32 v102, v112, v134, v135
	v_add_u32_e32 v112, 0xffffffa3, v103
	v_cmp_le_i32_e32 vcc, v112, v194
	v_add_u32_e32 v119, 0xffffffb2, v103
	s_nop 0
	v_cndmask_b32_e32 v137, v200, v120, vcc
	v_cmp_le_i32_e32 vcc, v118, v194
	s_nop 1
	v_cndmask_b32_e32 v136, v200, v121, vcc
	v_max3_f32 v120, v102, v137, v136
	v_mov_b32_e32 v102, s81
	v_cmp_gt_i32_e32 vcc, v113, v194
	v_add_u32_e32 v121, 0xffffffb4, v103
	s_nop 0
	v_cndmask_b32_e32 v138, v144, v102, vcc
	v_cmp_le_i32_e32 vcc, v119, v194
	s_nop 1
	v_cndmask_b32_e32 v139, v200, v145, vcc
	v_max3_f32 v102, v120, v138, v139
	v_add_u32_e32 v120, 0xffffffb3, v103
	v_cmp_le_i32_e32 vcc, v120, v194
	s_nop 1
	v_cndmask_b32_e32 v141, v200, v146, vcc
	v_cmp_le_i32_e32 vcc, v121, v194
	s_nop 1
	v_cndmask_b32_e32 v140, v200, v147, vcc
	v_max3_f32 v102, v102, v141, v140
	v_mov_b32_e32 v103, v102
	s_nop 1
	v_permlane16_swap_b32_e32 v102, v103
	v_max_f32_e32 v102, v102, v103
	v_mov_b32_e32 v103, v102
	s_nop 1
	v_permlane32_swap_b32_e32 v102, v103
	v_max_f32_e32 v102, v102, v103
	v_cmp_gt_f32_e32 vcc, v102, v1
	s_cbranch_vccz .LBB0_1004
	v_max_f32_e32 v1, v102, v102
	v_max_f32_e32 v102, v220, v220
	v_max_f32_e32 v102, v102, v1
	v_cmp_neq_f32_e32 vcc, s81, v102
	v_mov_b32_e32 v103, v221
	s_nop 0
	v_cndmask_b32_e32 v1, 0, v102, vcc
	v_sub_f32_e32 v1, v220, v1
	v_mul_f32_e32 v1, 0x3e16c740, v1
	v_exp_f32_e32 v144, v1
	v_mov_b64_e32 v[220:221], v[102:103]
	v_mul_f32_e32 v218, v218, v144
	v_pk_mul_f32 v[92:93], v[92:93], v[144:145] op_sel_hi:[1,0]
	v_pk_mul_f32 v[90:91], v[90:91], v[144:145] op_sel_hi:[1,0]
	v_pk_mul_f32 v[88:89], v[88:89], v[144:145] op_sel_hi:[1,0]
	v_pk_mul_f32 v[86:87], v[86:87], v[144:145] op_sel_hi:[1,0]
	v_pk_mul_f32 v[76:77], v[76:77], v[144:145] op_sel_hi:[1,0]
	v_pk_mul_f32 v[74:75], v[74:75], v[144:145] op_sel_hi:[1,0]
	v_pk_mul_f32 v[68:69], v[68:69], v[144:145] op_sel_hi:[1,0]
	v_pk_mul_f32 v[66:67], v[66:67], v[144:145] op_sel_hi:[1,0]
	s_branch .LBB0_1005

; #define LAS __attribute__((address_space(3)))
; #define LBAR() asm volatile("s_waitcnt lgkmcnt(0)\n\ts_barrier" ::: "memory")
; __device__ __forceinline__ f32x4 mfma16(bf16x8 a, bf16x8 b, f32x4 c) { return __builtin_amdgcn_mfma_f32_16x16x32_bf16(a, b, c, 0, 0, 0); }
;   __device__ __forceinline__ bf16_t* W() const { return (bf16_t*)(ws + WS_W); }
; template <int NT, int NKK, int NDT, int MODE, bool MASK> ...
;     ...
;   __builtin_amdgcn_s_setprio(1);
; #pragma unroll
;   for (int t = 0; t < 4; ++t)
; #pragma unroll
;     for (int kk = 0; kk < NKK; ++kk) {
;       const bf16x8 kf = *(LAS const bf16x8*)(Kl + (16 * t + r) * KSTR + (32 * kk + 8 * lg) * 2);
; #pragma unroll
;       for (int j = 0; j < NT; ++j) s[j][t] = mfma16(kf, qf[j][kk], kk == 0 ? (f32x4){0.f, 0.f, 0.f, 0.f} : s[j][t]);
;     }
;   __builtin_amdgcn_s_setprio(0);
;   bf16x8 pf[NT][2];
; #pragma unroll
;   for (int j = 0; j < NT; ++j) {
;     float mx = -INFINITY;
; #pragma unroll
;     for (int t = 0; t < 4; ++t)
; #pragma unroll
;       for (int i = 0; i < 4; ++i) {
;         if (MASK) { const int kp = kpos0 + 16 * t + 4 * lg + i; if (!mask_ok<MODE>(tq[j], kp, W)) s[j][t][i] = -INFINITY; }
;         mx = fmaxf(mx, s[j][t][i]);
;       }
;     mx = max_x16_x32(mx);
;     if (__any(mx > m[j] + 8.0f / c)) {
; template <int NT, int DQK, int DV, int MODE, int PD, class Src> ...
;     ...
;         LBAR();
;         const int lo = kbase + 64 * kc, hi = lo + 63;
;         bool rel = true, full = true;
;         if (MODE == MODE_CAUSAL) { rel = lo <= tq_max; full = hi <= tq_min; }
;         if (MODE == MODE_WINDOW) { rel = (lo <= tq_max) && (hi > tq_min - W); full = (hi <= tq_min) && (lo > tq_max - W); }
;         if (MODE == MODE_CMP) { rel = 16 * lo + 31 <= tq_max; full = 16 * hi + 31 <= tq_min; }
;         if (rel) {
;           if (NT <= 2) {
;             if (full) attn_chunk_wide<NT, DQK / 32, DV / 16, MODE, false>(o, m, l, qf, buf, KSTR, buf + KB, VSTR, lo, tq, c, W, lane);
;             else attn_chunk_wide<NT, DQK / 32, DV / 16, MODE, true>(o, m, l, qf, buf, KSTR, buf + KB, VSTR, lo, tq, c, W, lane);
.LBB0_1023:
	s_waitcnt lgkmcnt(0)
	s_barrier
	s_sub_i32 s8, s43, 63
	s_cmp_gt_i32 s8, s40
	s_cbranch_scc1 .LBB0_1050
	s_cmp_gt_i32 s43, s25
	s_setprio 1
	v_add_u32_e32 v1, s45, v236
	s_waitcnt lgkmcnt(0)
	v_add_u32_e32 v94, v1, v237
	ds_read_b128 v[134:137], v94
	ds_read_b128 v[130:133], v94 offset:64
	ds_read_b128 v[126:129], v94 offset:128
	ds_read_b128 v[122:125], v94 offset:3328
	ds_read_b128 v[118:121], v94 offset:3392
	ds_read_b128 v[114:117], v94 offset:3456
	ds_read_b128 v[106:109], v94 offset:6656
	ds_read_b128 v[98:101], v94 offset:6720
	v_add_u32_e32 v201, v1, v238
	ds_read_b128 v[110:113], v94 offset:6784
	ds_read_b128 v[102:105], v201
	ds_read_b128 v[94:97], v201 offset:64
	s_mov_b64 s[20:21], -1
	s_cbranch_scc1 .LBB0_1041
	s_waitcnt lgkmcnt(10)
	v_mfma_f32_16x16x32_bf16 v[138:141], v[134:137], v[18:21], 0
	v_add_f32_e32 v1, 0x4259535f, v220
	ds_read_b128 v[146:149], v201 offset:128
	v_mov_b32_e32 v234, 0x260
	v_mfma_f32_16x16x32_bf16 v[142:145], v[134:137], v[10:13], 0
	s_waitcnt lgkmcnt(10)
	v_mfma_f32_16x16x32_bf16 v[138:141], v[130:133], v[2:5], v[138:141]
	v_mov_b64_e32 v[222:223], v[220:221]
	v_mfma_f32_16x16x32_bf16 v[142:145], v[130:133], v[14:17], v[142:145]
	v_mov_b64_e32 v[224:225], v[218:219]
	s_waitcnt lgkmcnt(9)
	v_mfma_f32_16x16x32_bf16 v[182:185], v[126:129], v[6:9], v[138:141]
	v_mfma_f32_16x16x32_bf16 v[166:169], v[126:129], v[22:25], v[142:145]
	v_mov_b32_e32 v187, v220
	s_waitcnt lgkmcnt(8)
	v_mfma_f32_16x16x32_bf16 v[138:141], v[122:125], v[18:21], 0
	v_add_f32_e32 v158, 0x4259535f, v221
	v_mfma_f32_16x16x32_bf16 v[142:145], v[122:125], v[10:13], 0
	v_mul_f32_e32 v159, 0x3e16c740, v220
	s_waitcnt lgkmcnt(7)
	v_mfma_f32_16x16x32_bf16 v[138:141], v[118:121], v[2:5], v[138:141]
	v_cmp_neq_f32_e64 s[22:23], s81, v220
	v_mfma_f32_16x16x32_bf16 v[142:145], v[118:121], v[14:17], v[142:145]
	s_waitcnt lgkmcnt(6)
	v_mfma_f32_16x16x32_bf16 v[178:181], v[114:117], v[6:9], v[138:141]
	v_mfma_f32_16x16x32_bf16 v[154:157], v[114:117], v[22:25], v[142:145]
	v_cndmask_b32_e64 v159, 0, v159, s[22:23]
	s_waitcnt lgkmcnt(5)
	v_mfma_f32_16x16x32_bf16 v[138:141], v[106:109], v[18:21], 0
	v_mul_f32_e32 v160, 0x3e16c740, v221
	v_mfma_f32_16x16x32_bf16 v[142:145], v[106:109], v[10:13], 0
	v_cmp_neq_f32_e64 s[22:23], s81, v221
	v_max3_f32 v188, v182, s81, v183
	s_waitcnt lgkmcnt(4)
	v_mfma_f32_16x16x32_bf16 v[138:141], v[98:101], v[2:5], v[138:141]
	v_max3_f32 v188, v188, v184, v185
	v_mfma_f32_16x16x32_bf16 v[142:145], v[98:101], v[14:17], v[142:145]
	v_max3_f32 v189, v166, s81, v167
	s_waitcnt lgkmcnt(3)
	v_mfma_f32_16x16x32_bf16 v[174:177], v[110:113], v[6:9], v[138:141]
	v_cndmask_b32_e64 v160, 0, v160, s[22:23]
	v_max3_f32 v189, v189, v168, v169
	v_mfma_f32_16x16x32_bf16 v[150:153], v[110:113], v[22:25], v[142:145]
	s_waitcnt lgkmcnt(2)
	v_mfma_f32_16x16x32_bf16 v[138:141], v[102:105], v[18:21], 0
	v_mfma_f32_16x16x32_bf16 v[142:145], v[102:105], v[10:13], 0
	v_max3_f32 v188, v188, v178, v179
	s_waitcnt lgkmcnt(1)
	v_mfma_f32_16x16x32_bf16 v[138:141], v[94:97], v[2:5], v[138:141]
	v_max3_f32 v188, v188, v180, v181
	v_mfma_f32_16x16x32_bf16 v[142:145], v[94:97], v[14:17], v[142:145]
	v_max3_f32 v189, v189, v154, v155
	s_waitcnt lgkmcnt(0)
	v_mfma_f32_16x16x32_bf16 v[170:173], v[146:149], v[6:9], v[138:141]
	v_max3_f32 v189, v189, v156, v157
	v_mfma_f32_16x16x32_bf16 v[142:145], v[146:149], v[22:25], v[142:145]
	s_setprio 0
	s_nop 3
	v_max3_f32 v138, v188, v174, v175
	v_max3_f32 v138, v138, v176, v177
	v_max3_f32 v138, v138, v170, v171
	v_max3_f32 v138, v138, v172, v173
	v_mov_b32_e32 v139, v138
	s_nop 1
	v_permlane16_swap_b32_e32 v138, v139
	v_max_f32_e32 v138, v138, v139
	v_mov_b32_e32 v139, v138
	s_nop 1
	v_permlane32_swap_b32_e32 v138, v139
	v_max_f32_e32 v186, v138, v139
	v_cmp_gt_f32_e32 vcc, v186, v1
	s_cbranch_vccz .LBB0_1027
	v_max_f32_e32 v138, v186, v186
	v_max_f32_e32 v139, v220, v220
	v_max_f32_e32 v222, v139, v138
	v_cmp_neq_f32_e32 vcc, s81, v222
	v_mov_b32_e32 v223, v221
	v_mov_b32_e32 v225, v219
	v_cndmask_b32_e32 v138, 0, v222, vcc
	v_sub_f32_e32 v138, v220, v138
	v_mul_f32_e32 v138, 0x3e16c740, v138
	v_exp_f32_e32 v138, v138
	v_mov_b32_e32 v187, v222
	v_mul_f32_e32 v224, v218, v138
	v_pk_mul_f32 v[92:93], v[92:93], v[138:139] op_sel_hi:[1,0]
	v_pk_mul_f32 v[90:91], v[90:91], v[138:139] op_sel_hi:[1,0]
	v_pk_mul_f32 v[88:89], v[88:89], v[138:139] op_sel_hi:[1,0]
	v_pk_mul_f32 v[86:87], v[86:87], v[138:139] op_sel_hi:[1,0]
	v_pk_mul_f32 v[76:77], v[76:77], v[138:139] op_sel_hi:[1,0]
	v_pk_mul_f32 v[74:75], v[74:75], v[138:139] op_sel_hi:[1,0]
	v_pk_mul_f32 v[68:69], v[68:69], v[138:139] op_sel_hi:[1,0]
	v_pk_mul_f32 v[66:67], v[66:67], v[138:139] op_sel_hi:[1,0]
	v_mul_f32_e32 v159, 0x3e16c740, v187
	v_cmp_neq_f32_e32 vcc, s81, v187
	s_nop 1
	v_cndmask_b32_e32 v159, 0, v159, vcc

; #define LAS __attribute__((address_space(3)))
; __device__ __forceinline__ float ex2(float x) { return __builtin_amdgcn_exp2f(x); }
; __device__ __forceinline__ f32x4 mfma16(bf16x8 a, bf16x8 b, f32x4 c) { return __builtin_amdgcn_mfma_f32_16x16x32_bf16(a, b, c, 0, 0, 0); }
;   __device__ __forceinline__ bf16_t* W() const { return (bf16_t*)(ws + WS_W); }
; template <int NT, int NKK, int NDT, int MODE, bool MASK> ...
;     ...
;   __builtin_amdgcn_s_setprio(1);
; #pragma unroll
;   for (int t = 0; t < 4; ++t)
; #pragma unroll
;     for (int kk = 0; kk < NKK; ++kk) {
;       const bf16x8 kf = *(LAS const bf16x8*)(Kl + (16 * t + r) * KSTR + (32 * kk + 8 * lg) * 2);
; #pragma unroll
;       for (int j = 0; j < NT; ++j) s[j][t] = mfma16(kf, qf[j][kk], kk == 0 ? (f32x4){0.f, 0.f, 0.f, 0.f} : s[j][t]);
;     }
;   __builtin_amdgcn_s_setprio(0);
;   bf16x8 pf[NT][2];
; #pragma unroll
;   for (int j = 0; j < NT; ++j) {
;     float mx = -INFINITY;
; #pragma unroll
;     for (int t = 0; t < 4; ++t)
; #pragma unroll
;       for (int i = 0; i < 4; ++i) {
;         if (MASK) { const int kp = kpos0 + 16 * t + 4 * lg + i; if (!mask_ok<MODE>(tq[j], kp, W)) s[j][t][i] = -INFINITY; }
;         mx = fmaxf(mx, s[j][t][i]);
;       }
;     mx = max_x16_x32(mx);
;     if (__any(mx > m[j] + 8.0f / c)) {
;       const float mnew = fmaxf(m[j], mx);
;       const float ms2 = (mnew == -INFINITY) ? 0.f : mnew;
;       const float alpha = ex2((m[j] - ms2) * c);
;       m[j] = mnew; l[j] *= alpha;
; #pragma unroll
;       for (int dt = 0; dt < NDT; ++dt) o[j][dt] *= alpha;
;     }
.LBB0_1041:
	s_and_b64 vcc, exec, s[20:21]
	s_cbranch_vccz .LBB0_1049
	v_add_f32_e32 v1, 0x4259535f, v220
	s_waitcnt lgkmcnt(10)
	v_mfma_f32_16x16x32_bf16 v[138:141], v[134:137], v[18:21], 0
	v_mfma_f32_16x16x32_bf16 v[134:137], v[134:137], v[10:13], 0
	s_waitcnt lgkmcnt(9)
	v_mfma_f32_16x16x32_bf16 v[138:141], v[130:133], v[2:5], v[138:141]
	v_mfma_f32_16x16x32_bf16 v[134:137], v[130:133], v[14:17], v[134:137]
	s_waitcnt lgkmcnt(8)
	v_mfma_f32_16x16x32_bf16 v[130:133], v[126:129], v[6:9], v[138:141]
	v_mfma_f32_16x16x32_bf16 v[126:129], v[126:129], v[22:25], v[134:137]
	s_waitcnt lgkmcnt(7)
	v_mfma_f32_16x16x32_bf16 v[134:137], v[122:125], v[18:21], 0
	v_mfma_f32_16x16x32_bf16 v[122:125], v[122:125], v[10:13], 0
	s_waitcnt lgkmcnt(6)
	v_mfma_f32_16x16x32_bf16 v[134:137], v[118:121], v[2:5], v[134:137]
	v_mfma_f32_16x16x32_bf16 v[118:121], v[118:121], v[14:17], v[122:125]
	s_waitcnt lgkmcnt(5)
	v_mfma_f32_16x16x32_bf16 v[134:137], v[114:117], v[6:9], v[134:137]
	v_mfma_f32_16x16x32_bf16 v[114:117], v[114:117], v[22:25], v[118:121]
	s_waitcnt lgkmcnt(4)
	v_mfma_f32_16x16x32_bf16 v[118:121], v[106:109], v[18:21], 0
	v_mfma_f32_16x16x32_bf16 v[106:109], v[106:109], v[10:13], 0
	s_waitcnt lgkmcnt(3)
	v_mfma_f32_16x16x32_bf16 v[118:121], v[98:101], v[2:5], v[118:121]
	v_mfma_f32_16x16x32_bf16 v[98:101], v[98:101], v[14:17], v[106:109]
	s_waitcnt lgkmcnt(1)
	v_mfma_f32_16x16x32_bf16 v[106:109], v[102:105], v[18:21], 0
	v_mfma_f32_16x16x32_bf16 v[102:105], v[102:105], v[10:13], 0
	s_waitcnt lgkmcnt(0)
	v_mfma_f32_16x16x32_bf16 v[106:109], v[94:97], v[2:5], v[106:109]
	v_mfma_f32_16x16x32_bf16 v[94:97], v[94:97], v[14:17], v[102:105]
	s_nop 4
	ds_read_b128 v[102:105], v201 offset:128
	v_mfma_f32_16x16x32_bf16 v[118:121], v[110:113], v[6:9], v[118:121]
	v_mfma_f32_16x16x32_bf16 v[98:101], v[110:113], v[22:25], v[98:101]
	s_waitcnt lgkmcnt(0)
	v_mfma_f32_16x16x32_bf16 v[94:97], v[102:105], v[22:25], v[94:97]
	v_mfma_f32_16x16x32_bf16 v[144:147], v[102:105], v[6:9], v[106:109]
	s_setprio 0
	v_add_u32_e32 v103, s43, v241
	v_subrev_u32_e32 v104, 63, v103
	v_subrev_u32_e32 v105, 61, v103
	v_mov_b32_e32 v102, s81
	v_cmp_gt_i32_e64 s[20:21], v104, v194
	v_cmp_lt_i32_e64 s[22:23], v104, v194
	v_cmp_le_i32_e32 vcc, v105, v194
	v_subrev_u32_e32 v106, 60, v103
	v_cndmask_b32_e64 v142, v130, v102, s[20:21]
	v_cndmask_b32_e64 v122, v200, v131, s[22:23]
	v_cndmask_b32_e32 v124, v200, v132, vcc
	v_cmp_le_i32_e32 vcc, v106, v194
	v_max3_f32 v102, v142, s81, v122
	v_subrev_u32_e32 v107, 47, v103
	v_cndmask_b32_e32 v123, v200, v133, vcc
	v_max3_f32 v108, v102, v124, v123
	v_mov_b32_e32 v102, s81
	v_cmp_gt_i32_e32 vcc, v107, v194
	v_subrev_u32_e32 v107, 46, v103
	v_subrev_u32_e32 v110, 44, v103
	v_cndmask_b32_e32 v125, v134, v102, vcc
	v_cmp_le_i32_e32 vcc, v107, v194
	v_subrev_u32_e32 v109, 31, v103
	v_subrev_u32_e32 v111, 30, v103
	v_cndmask_b32_e32 v131, v200, v135, vcc
	v_max3_f32 v102, v108, v125, v131
	v_subrev_u32_e32 v108, 45, v103
	v_cmp_le_i32_e32 vcc, v108, v194
	v_add_u32_e32 v113, -15, v103
	s_nop 0
	v_cndmask_b32_e32 v133, v200, v136, vcc
	v_cmp_le_i32_e32 vcc, v110, v194
	s_nop 1
	v_cndmask_b32_e32 v132, v200, v137, vcc
	v_max3_f32 v112, v102, v133, v132
	v_mov_b32_e32 v102, s81
	v_cmp_gt_i32_e32 vcc, v109, v194
	s_nop 1
	v_cndmask_b32_e32 v134, v118, v102, vcc
	v_cmp_le_i32_e32 vcc, v111, v194
	v_subrev_u32_e32 v118, 28, v103
	s_nop 0
	v_cndmask_b32_e32 v135, v200, v119, vcc
	v_max3_f32 v102, v112, v134, v135
	v_subrev_u32_e32 v112, 29, v103
	v_cmp_le_i32_e32 vcc, v112, v194
	v_add_u32_e32 v119, -14, v103
	s_nop 0
	v_cndmask_b32_e32 v137, v200, v120, vcc
	v_cmp_le_i32_e32 vcc, v118, v194
	s_nop 1
	v_cndmask_b32_e32 v136, v200, v121, vcc
	v_max3_f32 v120, v102, v137, v136
	v_mov_b32_e32 v102, s81
	v_cmp_gt_i32_e32 vcc, v113, v194
	v_add_u32_e32 v121, -12, v103
	s_nop 0
	v_cndmask_b32_e32 v138, v144, v102, vcc
	v_cmp_le_i32_e32 vcc, v119, v194
	s_nop 1
	v_cndmask_b32_e32 v139, v200, v145, vcc
	v_max3_f32 v102, v120, v138, v139
	v_add_u32_e32 v120, -13, v103
	v_cmp_le_i32_e32 vcc, v120, v194
	s_nop 1
	v_cndmask_b32_e32 v141, v200, v146, vcc
	v_cmp_le_i32_e32 vcc, v121, v194
	s_nop 1
	v_cndmask_b32_e32 v140, v200, v147, vcc
	v_max3_f32 v102, v102, v141, v140
	v_mov_b32_e32 v103, v102
	s_nop 1
	v_permlane16_swap_b32_e32 v102, v103
	v_max_f32_e32 v102, v102, v103
	v_mov_b32_e32 v103, v102
	s_nop 1
	v_permlane32_swap_b32_e32 v102, v103
	v_max_f32_e32 v102, v102, v103
	v_cmp_gt_f32_e32 vcc, v102, v1
	s_cbranch_vccz .LBB0_1044
	v_max_f32_e32 v1, v102, v102
	v_max_f32_e32 v102, v220, v220
	v_max_f32_e32 v102, v102, v1
	v_cmp_neq_f32_e32 vcc, s81, v102
	v_mov_b32_e32 v103, v221
	s_nop 0
	v_cndmask_b32_e32 v1, 0, v102, vcc
	v_sub_f32_e32 v1, v220, v1
	v_mul_f32_e32 v1, 0x3e16c740, v1
	v_exp_f32_e32 v144, v1
	v_mov_b64_e32 v[220:221], v[102:103]
	v_mul_f32_e32 v218, v218, v144
	v_pk_mul_f32 v[92:93], v[92:93], v[144:145] op_sel_hi:[1,0]
	v_pk_mul_f32 v[90:91], v[90:91], v[144:145] op_sel_hi:[1,0]
	v_pk_mul_f32 v[88:89], v[88:89], v[144:145] op_sel_hi:[1,0]
	v_pk_mul_f32 v[86:87], v[86:87], v[144:145] op_sel_hi:[1,0]
	v_pk_mul_f32 v[76:77], v[76:77], v[144:145] op_sel_hi:[1,0]
	v_pk_mul_f32 v[74:75], v[74:75], v[144:145] op_sel_hi:[1,0]
	v_pk_mul_f32 v[68:69], v[68:69], v[144:145] op_sel_hi:[1,0]
	v_pk_mul_f32 v[66:67], v[66:67], v[144:145] op_sel_hi:[1,0]
	s_branch .LBB0_1045
